# GEMM MMA blocks: MFMA issue order changed to a snake over the (m,n) grid so consecutive MFMAs share one operand register set (bit-identical accumulation order per accumulator)
# speedup vs baseline: 1.0010x; 1.0010x over previous
.LBB0_309:
	ds_read_b128 v[146:149], v153
	ds_read_b128 v[160:163], v153 offset:1024
	ds_read_b128 v[164:167], v153 offset:2048
	ds_read_b128 v[168:171], v153 offset:3072
	ds_read_b128 v[172:175], v154
	ds_read_b128 v[176:179], v154 offset:1024
	ds_read_b128 v[180:183], v154 offset:2048
	ds_read_b128 v[184:187], v154 offset:3072
	s_add_u32 s34, s6, 0xfff00080
	s_addc_u32 s35, s7, -1
	s_cmp_eq_u32 s59, 60
	s_cselect_b32 s37, s5, s35
	s_cselect_b32 s36, s25, s34
	s_cselect_b32 s35, s23, s58
	s_cselect_b32 s34, s56, s57
	v_lshl_add_u64 v[220:221], s[6:7], 0, v[138:139]
	s_add_i32 m0, s31, 0xc000
	ds_read_b128 v[188:191], v155
	ds_read_b128 v[192:195], v155 offset:1024
	ds_read_b128 v[196:199], v155 offset:2048
	ds_read_b128 v[200:203], v155 offset:3072
	ds_read_b128 v[204:207], v155 offset:4096
	ds_read_b128 v[208:211], v155 offset:5120
	ds_read_b128 v[212:215], v155 offset:6144
	ds_read_b128 v[216:219], v155 offset:7168
	global_load_lds_dwordx4 v[220:221], off
	v_lshl_add_u64 v[220:221], s[6:7], 0, v[136:137]
	s_add_i32 m0, s31, 0xe000
	s_nop 0
	global_load_lds_dwordx4 v[220:221], off
	s_waitcnt vmcnt(8)
	s_waitcnt lgkmcnt(0)
	s_barrier
	s_setprio 1
	s_waitcnt lgkmcnt(0)
	v_mfma_f32_16x16x32_bf16 v[124:127], v[146:149], v[188:191], v[124:127]
	v_mfma_f32_16x16x32_bf16 v[120:123], v[164:167], v[188:191], v[120:123]
	v_mfma_f32_16x16x32_bf16 v[104:107], v[164:167], v[196:199], v[104:107]
	v_mfma_f32_16x16x32_bf16 v[108:111], v[146:149], v[196:199], v[108:111]
	v_mfma_f32_16x16x32_bf16 v[92:95], v[146:149], v[204:207], v[92:95]
	v_mfma_f32_16x16x32_bf16 v[88:91], v[164:167], v[204:207], v[88:91]
	v_mfma_f32_16x16x32_bf16 v[72:75], v[164:167], v[212:215], v[72:75]
	v_mfma_f32_16x16x32_bf16 v[76:79], v[146:149], v[212:215], v[76:79]
	v_mfma_f32_16x16x32_bf16 v[124:127], v[160:163], v[192:195], v[124:127]
	v_mfma_f32_16x16x32_bf16 v[120:123], v[168:171], v[192:195], v[120:123]
	v_mfma_f32_16x16x32_bf16 v[104:107], v[168:171], v[200:203], v[104:107]
	v_mfma_f32_16x16x32_bf16 v[108:111], v[160:163], v[200:203], v[108:111]
	v_mfma_f32_16x16x32_bf16 v[92:95], v[160:163], v[208:211], v[92:95]
	v_mfma_f32_16x16x32_bf16 v[88:91], v[168:171], v[208:211], v[88:91]
	v_mfma_f32_16x16x32_bf16 v[72:75], v[168:171], v[216:219], v[72:75]
	v_mfma_f32_16x16x32_bf16 v[76:79], v[160:163], v[216:219], v[76:79]
	s_setprio 0
	s_setprio 1
	v_mfma_f32_16x16x32_bf16 v[116:119], v[172:175], v[188:191], v[116:119]
	v_mfma_f32_16x16x32_bf16 v[112:115], v[180:183], v[188:191], v[112:115]
	v_mfma_f32_16x16x32_bf16 v[96:99], v[180:183], v[196:199], v[96:99]
	v_mfma_f32_16x16x32_bf16 v[100:103], v[172:175], v[196:199], v[100:103]
	v_mfma_f32_16x16x32_bf16 v[84:87], v[172:175], v[204:207], v[84:87]
	v_mfma_f32_16x16x32_bf16 v[80:83], v[180:183], v[204:207], v[80:83]
	v_mfma_f32_16x16x32_bf16 v[64:67], v[180:183], v[212:215], v[64:67]
	v_mfma_f32_16x16x32_bf16 v[68:71], v[172:175], v[212:215], v[68:71]
	v_mfma_f32_16x16x32_bf16 v[116:119], v[176:179], v[192:195], v[116:119]
	v_mfma_f32_16x16x32_bf16 v[112:115], v[184:187], v[192:195], v[112:115]
	v_mfma_f32_16x16x32_bf16 v[96:99], v[184:187], v[200:203], v[96:99]
	v_mfma_f32_16x16x32_bf16 v[100:103], v[176:179], v[200:203], v[100:103]
	v_mfma_f32_16x16x32_bf16 v[84:87], v[176:179], v[208:211], v[84:87]
	v_mfma_f32_16x16x32_bf16 v[80:83], v[184:187], v[208:211], v[80:83]
	v_mfma_f32_16x16x32_bf16 v[64:67], v[184:187], v[216:219], v[64:67]
	v_mfma_f32_16x16x32_bf16 v[68:71], v[176:179], v[216:219], v[68:71]
	s_setprio 0
	s_barrier
	s_add_i32 s60, s52, s42
	v_lshl_add_u64 v[220:221], s[34:35], 0, v[130:131]
	s_mov_b32 m0, s60
	ds_read_b128 v[188:191], v155 offset:16384
	ds_read_b128 v[192:195], v155 offset:17408
	ds_read_b128 v[196:199], v155 offset:18432
	ds_read_b128 v[200:203], v155 offset:19456
	ds_read_b128 v[204:207], v155 offset:20480
	ds_read_b128 v[208:211], v155 offset:21504
	ds_read_b128 v[212:215], v155 offset:22528
	ds_read_b128 v[216:219], v155 offset:23552
	global_load_lds_dwordx4 v[220:221], off
	s_add_i32 m0, s60, 0x2000
	s_add_u32 s60, s34, 0x100000
	v_lshl_add_u64 v[222:223], s[34:35], 0, v[134:135]
	s_addc_u32 s61, s35, 0
	s_add_i32 s62, s53, s42
	global_load_lds_dwordx4 v[222:223], off
	v_lshl_add_u64 v[224:225], s[60:61], 0, v[130:131]
	s_mov_b32 m0, s62
	v_lshl_add_u64 v[226:227], s[36:37], 0, v[132:133]
	global_load_lds_dwordx4 v[224:225], off
	v_lshl_add_u64 v[224:225], s[60:61], 0, v[134:135]
	s_add_i32 m0, s62, 0x2000
	s_nop 0
	global_load_lds_dwordx4 v[224:225], off
	v_lshl_add_u64 v[224:225], s[36:37], 0, v[128:129]
	s_mov_b32 m0, s31
	s_nop 0
	global_load_lds_dwordx4 v[224:225], off
	s_mov_b32 m0, s43
	s_nop 0
	global_load_lds_dwordx4 v[226:227], off
	s_waitcnt vmcnt(8)
	s_waitcnt lgkmcnt(0)
	s_barrier
	s_setprio 1
	s_waitcnt lgkmcnt(0)
	v_mfma_f32_16x16x32_bf16 v[60:63], v[146:149], v[188:191], v[60:63]
	v_mfma_f32_16x16x32_bf16 v[56:59], v[164:167], v[188:191], v[56:59]
	v_mfma_f32_16x16x32_bf16 v[40:43], v[164:167], v[196:199], v[40:43]
	v_mfma_f32_16x16x32_bf16 v[44:47], v[146:149], v[196:199], v[44:47]
	v_mfma_f32_16x16x32_bf16 v[28:31], v[146:149], v[204:207], v[28:31]
	v_mfma_f32_16x16x32_bf16 v[24:27], v[164:167], v[204:207], v[24:27]
	v_mfma_f32_16x16x32_bf16 v[8:11], v[164:167], v[212:215], v[8:11]
	v_mfma_f32_16x16x32_bf16 v[12:15], v[146:149], v[212:215], v[12:15]
	v_mfma_f32_16x16x32_bf16 v[60:63], v[160:163], v[192:195], v[60:63]
	v_mfma_f32_16x16x32_bf16 v[56:59], v[168:171], v[192:195], v[56:59]
	v_mfma_f32_16x16x32_bf16 v[40:43], v[168:171], v[200:203], v[40:43]
	v_mfma_f32_16x16x32_bf16 v[44:47], v[160:163], v[200:203], v[44:47]
	v_mfma_f32_16x16x32_bf16 v[28:31], v[160:163], v[208:211], v[28:31]
	v_mfma_f32_16x16x32_bf16 v[24:27], v[168:171], v[208:211], v[24:27]
	v_mfma_f32_16x16x32_bf16 v[8:11], v[168:171], v[216:219], v[8:11]
	v_mfma_f32_16x16x32_bf16 v[12:15], v[160:163], v[216:219], v[12:15]
	s_setprio 0
	s_setprio 1
	v_mfma_f32_16x16x32_bf16 v[52:55], v[172:175], v[188:191], v[52:55]
	v_mfma_f32_16x16x32_bf16 v[48:51], v[180:183], v[188:191], v[48:51]
	v_mfma_f32_16x16x32_bf16 v[32:35], v[180:183], v[196:199], v[32:35]
	v_mfma_f32_16x16x32_bf16 v[36:39], v[172:175], v[196:199], v[36:39]
	v_mfma_f32_16x16x32_bf16 v[20:23], v[172:175], v[204:207], v[20:23]
	v_mfma_f32_16x16x32_bf16 v[16:19], v[180:183], v[204:207], v[16:19]
	v_mfma_f32_16x16x32_bf16 v[0:3], v[180:183], v[212:215], v[0:3]
	v_mfma_f32_16x16x32_bf16 v[4:7], v[172:175], v[212:215], v[4:7]
	v_mfma_f32_16x16x32_bf16 v[52:55], v[176:179], v[192:195], v[52:55]
	v_mfma_f32_16x16x32_bf16 v[48:51], v[184:187], v[192:195], v[48:51]
	v_mfma_f32_16x16x32_bf16 v[32:35], v[184:187], v[200:203], v[32:35]
	v_mfma_f32_16x16x32_bf16 v[36:39], v[176:179], v[200:203], v[36:39]
	v_mfma_f32_16x16x32_bf16 v[20:23], v[176:179], v[208:211], v[20:23]
	v_mfma_f32_16x16x32_bf16 v[16:19], v[184:187], v[208:211], v[16:19]
	v_mfma_f32_16x16x32_bf16 v[0:3], v[184:187], v[216:219], v[0:3]
	v_mfma_f32_16x16x32_bf16 v[4:7], v[176:179], v[216:219], v[4:7]
	s_setprio 0
	s_barrier
	s_add_i32 s60, 0, 0x18000
	v_add_u32_e32 v144, s60, v151
	s_add_i32 s61, 0, 0x1c000
	ds_read_b128 v[146:149], v144
	ds_read_b128 v[160:163], v144 offset:1024
	ds_read_b128 v[164:167], v144 offset:2048
	ds_read_b128 v[168:171], v144 offset:3072
	v_add_u32_e32 v144, s61, v151
	ds_read_b128 v[172:175], v144
	ds_read_b128 v[176:179], v144 offset:1024
	ds_read_b128 v[180:183], v144 offset:2048
	ds_read_b128 v[184:187], v144 offset:3072
	s_add_u32 s36, s36, 0x100000
	s_addc_u32 s37, s37, 0
	s_mov_b32 m0, s44
	v_lshl_add_u64 v[228:229], s[36:37], 0, v[128:129]
	ds_read_b128 v[188:191], v155 offset:32768
	ds_read_b128 v[192:195], v155 offset:33792
	ds_read_b128 v[196:199], v155 offset:34816
	ds_read_b128 v[200:203], v155 offset:35840
	ds_read_b128 v[204:207], v155 offset:36864
	ds_read_b128 v[208:211], v155 offset:37888
	ds_read_b128 v[212:215], v155 offset:38912
	ds_read_b128 v[216:219], v155 offset:39936
	global_load_lds_dwordx4 v[228:229], off
	v_lshl_add_u64 v[228:229], s[36:37], 0, v[132:133]
	s_mov_b32 m0, s45
	s_nop 0
	global_load_lds_dwordx4 v[228:229], off
	s_waitcnt vmcnt(8)
	s_waitcnt lgkmcnt(0)
	s_barrier
	s_setprio 1
	s_waitcnt lgkmcnt(0)
	v_mfma_f32_16x16x32_bf16 v[124:127], v[146:149], v[188:191], v[124:127]
	v_mfma_f32_16x16x32_bf16 v[120:123], v[164:167], v[188:191], v[120:123]
	v_mfma_f32_16x16x32_bf16 v[104:107], v[164:167], v[196:199], v[104:107]
	v_mfma_f32_16x16x32_bf16 v[108:111], v[146:149], v[196:199], v[108:111]
	v_mfma_f32_16x16x32_bf16 v[92:95], v[146:149], v[204:207], v[92:95]
	v_mfma_f32_16x16x32_bf16 v[88:91], v[164:167], v[204:207], v[88:91]
	v_mfma_f32_16x16x32_bf16 v[72:75], v[164:167], v[212:215], v[72:75]
	v_mfma_f32_16x16x32_bf16 v[76:79], v[146:149], v[212:215], v[76:79]
	v_mfma_f32_16x16x32_bf16 v[124:127], v[160:163], v[192:195], v[124:127]
	v_mfma_f32_16x16x32_bf16 v[120:123], v[168:171], v[192:195], v[120:123]
	v_mfma_f32_16x16x32_bf16 v[104:107], v[168:171], v[200:203], v[104:107]
	v_mfma_f32_16x16x32_bf16 v[108:111], v[160:163], v[200:203], v[108:111]
	v_mfma_f32_16x16x32_bf16 v[92:95], v[160:163], v[208:211], v[92:95]
	v_mfma_f32_16x16x32_bf16 v[88:91], v[168:171], v[208:211], v[88:91]
	v_mfma_f32_16x16x32_bf16 v[72:75], v[168:171], v[216:219], v[72:75]
	v_mfma_f32_16x16x32_bf16 v[76:79], v[160:163], v[216:219], v[76:79]
	s_setprio 0
	s_setprio 1
	v_mfma_f32_16x16x32_bf16 v[116:119], v[172:175], v[188:191], v[116:119]
	v_mfma_f32_16x16x32_bf16 v[112:115], v[180:183], v[188:191], v[112:115]
	v_mfma_f32_16x16x32_bf16 v[96:99], v[180:183], v[196:199], v[96:99]
	v_mfma_f32_16x16x32_bf16 v[100:103], v[172:175], v[196:199], v[100:103]
	v_mfma_f32_16x16x32_bf16 v[84:87], v[172:175], v[204:207], v[84:87]
	v_mfma_f32_16x16x32_bf16 v[80:83], v[180:183], v[204:207], v[80:83]
	v_mfma_f32_16x16x32_bf16 v[64:67], v[180:183], v[212:215], v[64:67]
	v_mfma_f32_16x16x32_bf16 v[68:71], v[172:175], v[212:215], v[68:71]
	v_mfma_f32_16x16x32_bf16 v[116:119], v[176:179], v[192:195], v[116:119]
	v_mfma_f32_16x16x32_bf16 v[112:115], v[184:187], v[192:195], v[112:115]
	v_mfma_f32_16x16x32_bf16 v[96:99], v[184:187], v[200:203], v[96:99]
	v_mfma_f32_16x16x32_bf16 v[100:103], v[176:179], v[200:203], v[100:103]
	v_mfma_f32_16x16x32_bf16 v[84:87], v[176:179], v[208:211], v[84:87]
	v_mfma_f32_16x16x32_bf16 v[80:83], v[184:187], v[208:211], v[80:83]
	v_mfma_f32_16x16x32_bf16 v[64:67], v[184:187], v[216:219], v[64:67]
	v_mfma_f32_16x16x32_bf16 v[68:71], v[176:179], v[216:219], v[68:71]
	s_setprio 0
	s_barrier
	s_add_i32 s36, s60, s42
	v_lshl_add_u64 v[220:221], v[220:221], 0, s[16:17]
	s_mov_b32 m0, s36
	ds_read_b128 v[188:191], v155 offset:49152
	ds_read_b128 v[192:195], v155 offset:50176
	ds_read_b128 v[196:199], v155 offset:51200
	ds_read_b128 v[200:203], v155 offset:52224
	ds_read_b128 v[204:207], v155 offset:53248
	ds_read_b128 v[208:211], v155 offset:54272
	ds_read_b128 v[212:215], v155 offset:55296
	ds_read_b128 v[216:219], v155 offset:56320
	global_load_lds_dwordx4 v[220:221], off
	s_add_i32 m0, s36, 0x2000
	s_add_u32 s34, s34, 0x100080
	v_lshl_add_u64 v[220:221], v[222:223], 0, s[16:17]
	s_addc_u32 s35, s35, 0
	s_add_i32 s36, s61, s42
	global_load_lds_dwordx4 v[220:221], off
	v_lshl_add_u64 v[220:221], s[34:35], 0, v[130:131]
	s_mov_b32 m0, s36
	s_nop 0
	global_load_lds_dwordx4 v[220:221], off
	v_lshl_add_u64 v[220:221], s[34:35], 0, v[134:135]
	s_add_i32 m0, s36, 0x2000
	s_nop 0
	global_load_lds_dwordx4 v[220:221], off
	v_lshl_add_u64 v[220:221], v[224:225], 0, s[16:17]
	s_mov_b32 m0, s47
	s_nop 0
	global_load_lds_dwordx4 v[220:221], off
	v_lshl_add_u64 v[220:221], v[226:227], 0, s[16:17]
	s_mov_b32 m0, s48
	s_nop 0
	global_load_lds_dwordx4 v[220:221], off
	s_waitcnt vmcnt(8)
	s_waitcnt lgkmcnt(0)
	s_barrier
	s_setprio 1
	s_waitcnt lgkmcnt(0)
	v_mfma_f32_16x16x32_bf16 v[60:63], v[146:149], v[188:191], v[60:63]
	v_mfma_f32_16x16x32_bf16 v[56:59], v[164:167], v[188:191], v[56:59]
	v_mfma_f32_16x16x32_bf16 v[40:43], v[164:167], v[196:199], v[40:43]
	v_mfma_f32_16x16x32_bf16 v[44:47], v[146:149], v[196:199], v[44:47]
	v_mfma_f32_16x16x32_bf16 v[28:31], v[146:149], v[204:207], v[28:31]
	v_mfma_f32_16x16x32_bf16 v[24:27], v[164:167], v[204:207], v[24:27]
	v_mfma_f32_16x16x32_bf16 v[8:11], v[164:167], v[212:215], v[8:11]
	v_mfma_f32_16x16x32_bf16 v[12:15], v[146:149], v[212:215], v[12:15]
	v_mfma_f32_16x16x32_bf16 v[60:63], v[160:163], v[192:195], v[60:63]
	v_mfma_f32_16x16x32_bf16 v[56:59], v[168:171], v[192:195], v[56:59]
	v_mfma_f32_16x16x32_bf16 v[40:43], v[168:171], v[200:203], v[40:43]
	v_mfma_f32_16x16x32_bf16 v[44:47], v[160:163], v[200:203], v[44:47]
	v_mfma_f32_16x16x32_bf16 v[28:31], v[160:163], v[208:211], v[28:31]
	v_mfma_f32_16x16x32_bf16 v[24:27], v[168:171], v[208:211], v[24:27]
	v_mfma_f32_16x16x32_bf16 v[8:11], v[168:171], v[216:219], v[8:11]
	v_mfma_f32_16x16x32_bf16 v[12:15], v[160:163], v[216:219], v[12:15]
	s_setprio 0
	s_setprio 1
	v_mfma_f32_16x16x32_bf16 v[52:55], v[172:175], v[188:191], v[52:55]
	v_mfma_f32_16x16x32_bf16 v[48:51], v[180:183], v[188:191], v[48:51]
	v_mfma_f32_16x16x32_bf16 v[32:35], v[180:183], v[196:199], v[32:35]
	v_mfma_f32_16x16x32_bf16 v[36:39], v[172:175], v[196:199], v[36:39]
	v_mfma_f32_16x16x32_bf16 v[20:23], v[172:175], v[204:207], v[20:23]
	v_mfma_f32_16x16x32_bf16 v[16:19], v[180:183], v[204:207], v[16:19]
	v_mfma_f32_16x16x32_bf16 v[0:3], v[180:183], v[212:215], v[0:3]
	v_mfma_f32_16x16x32_bf16 v[4:7], v[172:175], v[212:215], v[4:7]
	v_mfma_f32_16x16x32_bf16 v[52:55], v[176:179], v[192:195], v[52:55]
	v_mfma_f32_16x16x32_bf16 v[48:51], v[184:187], v[192:195], v[48:51]
	v_mfma_f32_16x16x32_bf16 v[32:35], v[184:187], v[200:203], v[32:35]
	v_mfma_f32_16x16x32_bf16 v[36:39], v[176:179], v[200:203], v[36:39]
	v_mfma_f32_16x16x32_bf16 v[20:23], v[176:179], v[208:211], v[20:23]
	v_mfma_f32_16x16x32_bf16 v[16:19], v[184:187], v[208:211], v[16:19]
	v_mfma_f32_16x16x32_bf16 v[0:3], v[184:187], v[216:219], v[0:3]
	v_mfma_f32_16x16x32_bf16 v[4:7], v[176:179], v[216:219], v[4:7]
	s_setprio 0
	s_barrier
	s_add_i32 s59, s59, 2
	s_add_u32 s57, s57, 0x100
	s_addc_u32 s58, s58, 0
	s_add_u32 s6, s6, 0x100
	s_addc_u32 s7, s7, 0
	s_cmp_gt_u32 s59, 61
	s_cbranch_scc0 .LBB0_309
	s_and_b64 vcc, exec, s[18:19]
	s_cbranch_vccz .LBB0_312
	s_barrier

.LBB0_618:
	s_ashr_i32 s35, s34, 31
	s_lshl_b64 s[36:37], s[34:35], 19
	s_add_u32 s31, s33, s36
	s_addc_u32 s35, s50, s37
	s_ashr_i32 s36, s30, 3
	ds_read_b128 v[0:3], v155
	ds_read_b128 v[4:7], v155 offset:1024
	ds_read_b128 v[8:11], v155 offset:2048
	ds_read_b128 v[12:15], v155 offset:3072
	ds_read_b128 v[16:19], v156
	ds_read_b128 v[20:23], v156 offset:1024
	ds_read_b128 v[24:27], v156 offset:2048
	ds_read_b128 v[28:31], v156 offset:3072
	s_ashr_i32 s37, s36, 31
	s_lshl_b64 s[36:37], s[36:37], 9
	s_add_u32 s36, s31, s36
	s_addc_u32 s37, s35, s37
	s_and_b64 s[38:39], s[2:3], exec
	s_cselect_b32 s49, s37, s43
	s_cselect_b32 s48, s36, s42
	s_ashr_i32 s31, s30, 31
	s_lshl_b64 s[38:39], s[30:31], 17
	s_add_u32 s38, s51, s38
	s_addc_u32 s39, s52, s39
	s_and_b64 s[46:47], s[2:3], exec
	s_cselect_b32 s47, s39, s45
	s_cselect_b32 s46, s38, s44
	s_add_u32 s74, s42, 0x40080
	s_addc_u32 s75, s43, 0
	s_add_i32 s77, s60, 0xc000
	v_lshl_add_u64 v[64:65], s[74:75], 0, v[134:135]
	s_mov_b32 m0, s77
	s_add_i32 s31, s60, 0xe000
	ds_read_b128 v[32:35], v157
	ds_read_b128 v[36:39], v157 offset:1024
	ds_read_b128 v[40:43], v157 offset:2048
	ds_read_b128 v[44:47], v157 offset:3072
	ds_read_b128 v[48:51], v157 offset:4096
	ds_read_b128 v[52:55], v157 offset:5120
	ds_read_b128 v[56:59], v157 offset:6144
	ds_read_b128 v[60:63], v157 offset:7168
	global_load_lds_dwordx4 v[64:65], off
	v_lshl_add_u64 v[64:65], s[74:75], 0, v[130:131]
	s_mov_b32 m0, s31
	s_nop 0
	global_load_lds_dwordx4 v[64:65], off
	s_waitcnt vmcnt(8)
	s_waitcnt lgkmcnt(0)
	s_barrier
	s_setprio 1
	s_waitcnt lgkmcnt(0)
	v_mfma_f32_16x16x32_bf16 v[64:67], v[0:3], v[32:35], 0
	v_mfma_f32_16x16x32_bf16 v[68:71], v[8:11], v[32:35], 0
	v_mfma_f32_16x16x32_bf16 v[72:75], v[0:3], v[40:43], 0
	v_mfma_f32_16x16x32_bf16 v[76:79], v[8:11], v[40:43], 0
	v_mfma_f32_16x16x32_bf16 v[80:83], v[0:3], v[48:51], 0
	v_mfma_f32_16x16x32_bf16 v[84:87], v[8:11], v[48:51], 0
	v_mfma_f32_16x16x32_bf16 v[88:91], v[0:3], v[56:59], 0
	v_mfma_f32_16x16x32_bf16 v[92:95], v[8:11], v[56:59], 0
	v_mfma_f32_16x16x32_bf16 v[64:67], v[4:7], v[36:39], v[64:67]
	v_mfma_f32_16x16x32_bf16 v[68:71], v[12:15], v[36:39], v[68:71]
	v_mfma_f32_16x16x32_bf16 v[76:79], v[12:15], v[44:47], v[76:79]
	v_mfma_f32_16x16x32_bf16 v[72:75], v[4:7], v[44:47], v[72:75]
	v_mfma_f32_16x16x32_bf16 v[80:83], v[4:7], v[52:55], v[80:83]
	v_mfma_f32_16x16x32_bf16 v[84:87], v[12:15], v[52:55], v[84:87]
	v_mfma_f32_16x16x32_bf16 v[92:95], v[12:15], v[60:63], v[92:95]
	v_mfma_f32_16x16x32_bf16 v[88:91], v[4:7], v[60:63], v[88:91]
	s_setprio 0
	s_setprio 1
	v_mfma_f32_16x16x32_bf16 v[96:99], v[16:19], v[32:35], 0
	v_mfma_f32_16x16x32_bf16 v[32:35], v[24:27], v[32:35], 0
	v_mfma_f32_16x16x32_bf16 v[96:99], v[20:23], v[36:39], v[96:99]
	v_mfma_f32_16x16x32_bf16 v[32:35], v[28:31], v[36:39], v[32:35]
	v_mfma_f32_16x16x32_bf16 v[36:39], v[16:19], v[40:43], 0
	v_mfma_f32_16x16x32_bf16 v[40:43], v[24:27], v[40:43], 0
	v_mfma_f32_16x16x32_bf16 v[36:39], v[20:23], v[44:47], v[36:39]
	v_mfma_f32_16x16x32_bf16 v[40:43], v[28:31], v[44:47], v[40:43]
	v_mfma_f32_16x16x32_bf16 v[44:47], v[16:19], v[48:51], 0
	v_mfma_f32_16x16x32_bf16 v[48:51], v[24:27], v[48:51], 0
	v_mfma_f32_16x16x32_bf16 v[44:47], v[20:23], v[52:55], v[44:47]
	v_mfma_f32_16x16x32_bf16 v[48:51], v[28:31], v[52:55], v[48:51]
	v_mfma_f32_16x16x32_bf16 v[52:55], v[16:19], v[56:59], 0
	v_mfma_f32_16x16x32_bf16 v[56:59], v[24:27], v[56:59], 0
	v_mfma_f32_16x16x32_bf16 v[52:55], v[20:23], v[60:63], v[52:55]
	v_mfma_f32_16x16x32_bf16 v[56:59], v[28:31], v[60:63], v[56:59]
	s_setprio 0
	s_barrier
	s_add_i32 s75, s67, s53
	v_lshl_add_u64 v[210:211], s[44:45], 0, v[132:133]
	s_add_i32 s35, s75, 0x2000
	v_lshl_add_u64 v[140:141], v[210:211], 0, s[18:19]
	s_mov_b32 m0, s75
	v_lshl_add_u64 v[212:213], s[44:45], 0, v[128:129]
	s_add_u32 s78, s44, 0x10100
	ds_read_b128 v[60:63], v157 offset:16384
	ds_read_b128 v[100:103], v157 offset:17408
	ds_read_b128 v[104:107], v157 offset:18432
	ds_read_b128 v[108:111], v157 offset:19456
	ds_read_b128 v[112:115], v157 offset:20480
	ds_read_b128 v[116:119], v157 offset:21504
	ds_read_b128 v[120:123], v157 offset:22528
	ds_read_b128 v[124:127], v157 offset:23552
	global_load_lds_dwordx4 v[140:141], off
	v_lshl_add_u64 v[140:141], v[212:213], 0, s[18:19]
	s_mov_b32 m0, s35
	s_addc_u32 s79, s45, 0
	s_add_i32 s41, s68, s53
	global_load_lds_dwordx4 v[140:141], off
	v_lshl_add_u64 v[140:141], s[78:79], 0, v[132:133]
	s_mov_b32 m0, s41
	s_add_i32 s74, s41, 0x2000
	global_load_lds_dwordx4 v[140:141], off
	v_lshl_add_u64 v[140:141], s[78:79], 0, v[128:129]
	s_mov_b32 m0, s74
	v_lshl_add_u64 v[214:215], s[42:43], 0, v[134:135]
	global_load_lds_dwordx4 v[140:141], off
	v_lshl_add_u64 v[140:141], v[214:215], 0, s[18:19]
	s_mov_b32 m0, s60
	v_lshl_add_u64 v[216:217], s[42:43], 0, v[130:131]
	global_load_lds_dwordx4 v[140:141], off
	v_lshl_add_u64 v[140:141], v[216:217], 0, s[18:19]
	s_mov_b32 m0, s61
	s_nop 0
	global_load_lds_dwordx4 v[140:141], off
	s_waitcnt vmcnt(8)
	s_waitcnt lgkmcnt(0)
	s_barrier
	s_setprio 1
	s_waitcnt lgkmcnt(0)
	v_mfma_f32_16x16x32_bf16 v[140:143], v[0:3], v[60:63], 0
	v_mfma_f32_16x16x32_bf16 v[148:151], v[0:3], v[104:107], 0
	v_mfma_f32_16x16x32_bf16 v[162:165], v[0:3], v[112:115], 0
	v_mfma_f32_16x16x32_bf16 v[0:3], v[0:3], v[120:123], 0
	v_mfma_f32_16x16x32_bf16 v[140:143], v[4:7], v[100:103], v[140:143]
	v_mfma_f32_16x16x32_bf16 v[148:151], v[4:7], v[108:111], v[148:151]
	v_mfma_f32_16x16x32_bf16 v[162:165], v[4:7], v[116:119], v[162:165]
	v_mfma_f32_16x16x32_bf16 v[0:3], v[4:7], v[124:127], v[0:3]
	v_mfma_f32_16x16x32_bf16 v[4:7], v[8:11], v[120:123], 0
	v_mfma_f32_16x16x32_bf16 v[144:147], v[8:11], v[60:63], 0
	v_mfma_f32_16x16x32_bf16 v[158:161], v[8:11], v[104:107], 0
	v_mfma_f32_16x16x32_bf16 v[166:169], v[8:11], v[112:115], 0
	v_mfma_f32_16x16x32_bf16 v[4:7], v[12:15], v[124:127], v[4:7]
	v_mfma_f32_16x16x32_bf16 v[144:147], v[12:15], v[100:103], v[144:147]
	v_mfma_f32_16x16x32_bf16 v[158:161], v[12:15], v[108:111], v[158:161]
	v_mfma_f32_16x16x32_bf16 v[166:169], v[12:15], v[116:119], v[166:169]
	s_setprio 0
	s_setprio 1
	v_mfma_f32_16x16x32_bf16 v[8:11], v[16:19], v[60:63], 0
	v_mfma_f32_16x16x32_bf16 v[12:15], v[24:27], v[60:63], 0
	v_mfma_f32_16x16x32_bf16 v[8:11], v[20:23], v[100:103], v[8:11]
	v_mfma_f32_16x16x32_bf16 v[12:15], v[28:31], v[100:103], v[12:15]
	v_mfma_f32_16x16x32_bf16 v[60:63], v[16:19], v[104:107], 0
	v_mfma_f32_16x16x32_bf16 v[100:103], v[24:27], v[104:107], 0
	v_mfma_f32_16x16x32_bf16 v[104:107], v[16:19], v[112:115], 0
	v_mfma_f32_16x16x32_bf16 v[16:19], v[16:19], v[120:123], 0
	v_mfma_f32_16x16x32_bf16 v[60:63], v[20:23], v[108:111], v[60:63]
	v_mfma_f32_16x16x32_bf16 v[100:103], v[28:31], v[108:111], v[100:103]
	v_mfma_f32_16x16x32_bf16 v[104:107], v[20:23], v[116:119], v[104:107]
	v_mfma_f32_16x16x32_bf16 v[108:111], v[24:27], v[112:115], 0
	v_mfma_f32_16x16x32_bf16 v[16:19], v[20:23], v[124:127], v[16:19]
	v_mfma_f32_16x16x32_bf16 v[20:23], v[24:27], v[120:123], 0
	v_mfma_f32_16x16x32_bf16 v[108:111], v[28:31], v[116:119], v[108:111]
	v_mfma_f32_16x16x32_bf16 v[20:23], v[28:31], v[124:127], v[20:23]
	s_setprio 0
	s_barrier
	s_add_i32 s76, 0, 0x18000
	s_add_i32 s82, 0, 0x1c000
	v_add_u32_e32 v136, s76, v153
	v_add_u32_e32 v226, s82, v153
	ds_read_b128 v[24:27], v136
	ds_read_b128 v[28:31], v136 offset:1024
	ds_read_b128 v[112:115], v136 offset:2048
	ds_read_b128 v[116:119], v136 offset:3072
	ds_read_b128 v[120:123], v226
	ds_read_b128 v[124:127], v226 offset:1024
	ds_read_b128 v[170:173], v226 offset:2048
	ds_read_b128 v[174:177], v226 offset:3072
	s_add_u32 s78, s42, 0x40100
	s_addc_u32 s79, s43, 0
	s_mov_b32 m0, s62
	v_lshl_add_u64 v[218:219], s[78:79], 0, v[134:135]
	ds_read_b128 v[178:181], v157 offset:32768
	ds_read_b128 v[182:185], v157 offset:33792
	ds_read_b128 v[186:189], v157 offset:34816
	ds_read_b128 v[190:193], v157 offset:35840
	ds_read_b128 v[194:197], v157 offset:36864
	ds_read_b128 v[198:201], v157 offset:37888
	ds_read_b128 v[202:205], v157 offset:38912
	ds_read_b128 v[206:209], v157 offset:39936
	global_load_lds_dwordx4 v[218:219], off
	v_lshl_add_u64 v[218:219], s[78:79], 0, v[130:131]
	s_mov_b32 m0, s63
	s_nop 0
	global_load_lds_dwordx4 v[218:219], off
	s_waitcnt vmcnt(8)
	s_waitcnt lgkmcnt(0)
	s_barrier
	s_setprio 1
	s_waitcnt lgkmcnt(0)
	v_mfma_f32_16x16x32_bf16 v[64:67], v[24:27], v[178:181], v[64:67]
	v_mfma_f32_16x16x32_bf16 v[68:71], v[112:115], v[178:181], v[68:71]
	v_mfma_f32_16x16x32_bf16 v[76:79], v[112:115], v[186:189], v[76:79]
	v_mfma_f32_16x16x32_bf16 v[72:75], v[24:27], v[186:189], v[72:75]
	v_mfma_f32_16x16x32_bf16 v[80:83], v[24:27], v[194:197], v[80:83]
	v_mfma_f32_16x16x32_bf16 v[84:87], v[112:115], v[194:197], v[84:87]
	v_mfma_f32_16x16x32_bf16 v[92:95], v[112:115], v[202:205], v[92:95]
	v_mfma_f32_16x16x32_bf16 v[88:91], v[24:27], v[202:205], v[88:91]
	v_mfma_f32_16x16x32_bf16 v[64:67], v[28:31], v[182:185], v[64:67]
	v_mfma_f32_16x16x32_bf16 v[68:71], v[116:119], v[182:185], v[68:71]
	v_mfma_f32_16x16x32_bf16 v[76:79], v[116:119], v[190:193], v[76:79]
	v_mfma_f32_16x16x32_bf16 v[72:75], v[28:31], v[190:193], v[72:75]
	v_mfma_f32_16x16x32_bf16 v[80:83], v[28:31], v[198:201], v[80:83]
	v_mfma_f32_16x16x32_bf16 v[84:87], v[116:119], v[198:201], v[84:87]
	v_mfma_f32_16x16x32_bf16 v[92:95], v[116:119], v[206:209], v[92:95]
	v_mfma_f32_16x16x32_bf16 v[88:91], v[28:31], v[206:209], v[88:91]
	s_setprio 0
	s_setprio 1
	v_mfma_f32_16x16x32_bf16 v[96:99], v[120:123], v[178:181], v[96:99]
	v_mfma_f32_16x16x32_bf16 v[32:35], v[170:173], v[178:181], v[32:35]
	v_mfma_f32_16x16x32_bf16 v[40:43], v[170:173], v[186:189], v[40:43]
	v_mfma_f32_16x16x32_bf16 v[36:39], v[120:123], v[186:189], v[36:39]
	v_mfma_f32_16x16x32_bf16 v[44:47], v[120:123], v[194:197], v[44:47]
	v_mfma_f32_16x16x32_bf16 v[48:51], v[170:173], v[194:197], v[48:51]
	v_mfma_f32_16x16x32_bf16 v[56:59], v[170:173], v[202:205], v[56:59]
	v_mfma_f32_16x16x32_bf16 v[52:55], v[120:123], v[202:205], v[52:55]
	v_mfma_f32_16x16x32_bf16 v[96:99], v[124:127], v[182:185], v[96:99]
	v_mfma_f32_16x16x32_bf16 v[32:35], v[174:177], v[182:185], v[32:35]
	v_mfma_f32_16x16x32_bf16 v[40:43], v[174:177], v[190:193], v[40:43]
	v_mfma_f32_16x16x32_bf16 v[36:39], v[124:127], v[190:193], v[36:39]
	v_mfma_f32_16x16x32_bf16 v[44:47], v[124:127], v[198:201], v[44:47]
	v_mfma_f32_16x16x32_bf16 v[48:51], v[174:177], v[198:201], v[48:51]
	v_mfma_f32_16x16x32_bf16 v[56:59], v[174:177], v[206:209], v[56:59]
	v_mfma_f32_16x16x32_bf16 v[52:55], v[124:127], v[206:209], v[52:55]
	s_setprio 0
	s_barrier
	s_add_i32 s78, s76, s53
	s_add_i32 s76, s78, 0x2000
	v_lshl_add_u64 v[210:211], v[210:211], 0, s[20:21]
	s_mov_b32 m0, s78
	s_add_u32 s80, s44, 0x10180
	ds_read_b128 v[178:181], v157 offset:49152
	ds_read_b128 v[182:185], v157 offset:50176
	ds_read_b128 v[186:189], v157 offset:51200
	ds_read_b128 v[190:193], v157 offset:52224
	ds_read_b128 v[194:197], v157 offset:53248
	ds_read_b128 v[198:201], v157 offset:54272
	ds_read_b128 v[202:205], v157 offset:55296
	ds_read_b128 v[206:209], v157 offset:56320
	global_load_lds_dwordx4 v[210:211], off
	v_lshl_add_u64 v[210:211], v[212:213], 0, s[20:21]
	s_mov_b32 m0, s76
	s_addc_u32 s81, s45, 0
	s_add_i32 s44, s82, s53
	global_load_lds_dwordx4 v[210:211], off
	v_lshl_add_u64 v[210:211], s[80:81], 0, v[132:133]
	s_mov_b32 m0, s44
	s_add_i32 s45, s44, 0x2000
	global_load_lds_dwordx4 v[210:211], off
	v_lshl_add_u64 v[210:211], s[80:81], 0, v[128:129]
	s_mov_b32 m0, s45
	s_nop 0
	global_load_lds_dwordx4 v[210:211], off
	v_lshl_add_u64 v[210:211], v[214:215], 0, s[20:21]
	s_mov_b32 m0, s64
	s_nop 0
	global_load_lds_dwordx4 v[210:211], off
	v_lshl_add_u64 v[210:211], v[216:217], 0, s[20:21]
	s_mov_b32 m0, s65
	s_nop 0
	global_load_lds_dwordx4 v[210:211], off
	s_waitcnt vmcnt(8)
	s_waitcnt lgkmcnt(0)
	s_barrier
	s_setprio 1
	s_waitcnt lgkmcnt(0)
	v_mfma_f32_16x16x32_bf16 v[0:3], v[24:27], v[202:205], v[0:3]
	v_mfma_f32_16x16x32_bf16 v[4:7], v[112:115], v[202:205], v[4:7]
	v_mfma_f32_16x16x32_bf16 v[144:147], v[112:115], v[178:181], v[144:147]
	v_mfma_f32_16x16x32_bf16 v[140:143], v[24:27], v[178:181], v[140:143]
	v_mfma_f32_16x16x32_bf16 v[148:151], v[24:27], v[186:189], v[148:151]
	v_mfma_f32_16x16x32_bf16 v[158:161], v[112:115], v[186:189], v[158:161]
	v_mfma_f32_16x16x32_bf16 v[166:169], v[112:115], v[194:197], v[166:169]
	v_mfma_f32_16x16x32_bf16 v[162:165], v[24:27], v[194:197], v[162:165]
	v_mfma_f32_16x16x32_bf16 v[0:3], v[28:31], v[206:209], v[0:3]
	v_mfma_f32_16x16x32_bf16 v[4:7], v[116:119], v[206:209], v[4:7]
	v_mfma_f32_16x16x32_bf16 v[144:147], v[116:119], v[182:185], v[144:147]
	v_mfma_f32_16x16x32_bf16 v[140:143], v[28:31], v[182:185], v[140:143]
	v_mfma_f32_16x16x32_bf16 v[148:151], v[28:31], v[190:193], v[148:151]
	v_mfma_f32_16x16x32_bf16 v[158:161], v[116:119], v[190:193], v[158:161]
	v_mfma_f32_16x16x32_bf16 v[166:169], v[116:119], v[198:201], v[166:169]
	v_mfma_f32_16x16x32_bf16 v[162:165], v[28:31], v[198:201], v[162:165]
	s_setprio 0
	s_setprio 1
	v_mfma_f32_16x16x32_bf16 v[8:11], v[120:123], v[178:181], v[8:11]
	v_mfma_f32_16x16x32_bf16 v[12:15], v[170:173], v[178:181], v[12:15]
	v_mfma_f32_16x16x32_bf16 v[28:31], v[170:173], v[186:189], v[100:103]
	v_mfma_f32_16x16x32_bf16 v[24:27], v[120:123], v[186:189], v[60:63]
	v_mfma_f32_16x16x32_bf16 v[60:63], v[120:123], v[194:197], v[104:107]
	v_mfma_f32_16x16x32_bf16 v[100:103], v[170:173], v[194:197], v[108:111]
	v_mfma_f32_16x16x32_bf16 v[20:23], v[170:173], v[202:205], v[20:23]
	v_mfma_f32_16x16x32_bf16 v[16:19], v[120:123], v[202:205], v[16:19]
	v_mfma_f32_16x16x32_bf16 v[8:11], v[124:127], v[182:185], v[8:11]
	v_mfma_f32_16x16x32_bf16 v[12:15], v[174:177], v[182:185], v[12:15]
	v_mfma_f32_16x16x32_bf16 v[28:31], v[174:177], v[190:193], v[28:31]
	v_mfma_f32_16x16x32_bf16 v[24:27], v[124:127], v[190:193], v[24:27]
	v_mfma_f32_16x16x32_bf16 v[60:63], v[124:127], v[198:201], v[60:63]
	v_mfma_f32_16x16x32_bf16 v[100:103], v[174:177], v[198:201], v[100:103]
	v_mfma_f32_16x16x32_bf16 v[20:23], v[174:177], v[206:209], v[20:23]
	v_mfma_f32_16x16x32_bf16 v[16:19], v[124:127], v[206:209], v[16:19]
	s_setprio 0
	s_barrier
	ds_read_b128 v[104:107], v155
	ds_read_b128 v[108:111], v155 offset:1024
	ds_read_b128 v[112:115], v155 offset:2048
	ds_read_b128 v[116:119], v155 offset:3072
	ds_read_b128 v[120:123], v156
	ds_read_b128 v[124:127], v156 offset:1024
	ds_read_b128 v[170:173], v156 offset:2048
	ds_read_b128 v[174:177], v156 offset:3072
	s_add_u32 s42, s42, 0x40180
	s_addc_u32 s43, s43, 0
	s_mov_b32 m0, s77
	v_lshl_add_u64 v[210:211], s[42:43], 0, v[134:135]
	ds_read_b128 v[178:181], v157
	ds_read_b128 v[182:185], v157 offset:1024
	ds_read_b128 v[186:189], v157 offset:2048
	ds_read_b128 v[190:193], v157 offset:3072
	ds_read_b128 v[194:197], v157 offset:4096
	ds_read_b128 v[198:201], v157 offset:5120
	ds_read_b128 v[202:205], v157 offset:6144
	ds_read_b128 v[206:209], v157 offset:7168
	global_load_lds_dwordx4 v[210:211], off
	v_lshl_add_u64 v[210:211], s[42:43], 0, v[130:131]
	s_mov_b32 m0, s31
	s_nop 0
	global_load_lds_dwordx4 v[210:211], off
	s_waitcnt vmcnt(8)
	s_waitcnt lgkmcnt(0)
	s_barrier
	s_setprio 1
	s_waitcnt lgkmcnt(0)
	v_mfma_f32_16x16x32_bf16 v[64:67], v[104:107], v[178:181], v[64:67]
	v_mfma_f32_16x16x32_bf16 v[68:71], v[112:115], v[178:181], v[68:71]
	v_mfma_f32_16x16x32_bf16 v[76:79], v[112:115], v[186:189], v[76:79]
	v_mfma_f32_16x16x32_bf16 v[72:75], v[104:107], v[186:189], v[72:75]
	v_mfma_f32_16x16x32_bf16 v[80:83], v[104:107], v[194:197], v[80:83]
	v_mfma_f32_16x16x32_bf16 v[84:87], v[112:115], v[194:197], v[84:87]
	v_mfma_f32_16x16x32_bf16 v[92:95], v[112:115], v[202:205], v[92:95]
	v_mfma_f32_16x16x32_bf16 v[88:91], v[104:107], v[202:205], v[88:91]
	v_mfma_f32_16x16x32_bf16 v[64:67], v[108:111], v[182:185], v[64:67]
	v_mfma_f32_16x16x32_bf16 v[68:71], v[116:119], v[182:185], v[68:71]
	v_mfma_f32_16x16x32_bf16 v[76:79], v[116:119], v[190:193], v[76:79]
	v_mfma_f32_16x16x32_bf16 v[72:75], v[108:111], v[190:193], v[72:75]
	v_mfma_f32_16x16x32_bf16 v[80:83], v[108:111], v[198:201], v[80:83]
	v_mfma_f32_16x16x32_bf16 v[84:87], v[116:119], v[198:201], v[84:87]
	v_mfma_f32_16x16x32_bf16 v[92:95], v[116:119], v[206:209], v[92:95]
	v_mfma_f32_16x16x32_bf16 v[88:91], v[108:111], v[206:209], v[88:91]
	s_setprio 0
	s_setprio 1
	v_mfma_f32_16x16x32_bf16 v[32:35], v[170:173], v[178:181], v[32:35]
	v_mfma_f32_16x16x32_bf16 v[96:99], v[120:123], v[178:181], v[96:99]
	v_mfma_f32_16x16x32_bf16 v[178:181], v[174:177], v[182:185], v[32:35]
	v_mfma_f32_16x16x32_bf16 v[32:35], v[120:123], v[186:189], v[36:39]
	v_mfma_f32_16x16x32_bf16 v[96:99], v[124:127], v[182:185], v[96:99]
	v_mfma_f32_16x16x32_bf16 v[182:185], v[124:127], v[190:193], v[32:35]
	v_mfma_f32_16x16x32_bf16 v[32:35], v[170:173], v[186:189], v[40:43]
	v_mfma_f32_16x16x32_bf16 v[40:43], v[174:177], v[190:193], v[32:35]
	v_mfma_f32_16x16x32_bf16 v[32:35], v[120:123], v[194:197], v[44:47]
	v_mfma_f32_16x16x32_bf16 v[44:47], v[124:127], v[198:201], v[32:35]
	v_mfma_f32_16x16x32_bf16 v[32:35], v[170:173], v[194:197], v[48:51]
	v_mfma_f32_16x16x32_bf16 v[186:189], v[174:177], v[198:201], v[32:35]
	v_mfma_f32_16x16x32_bf16 v[32:35], v[120:123], v[202:205], v[52:55]
	v_mfma_f32_16x16x32_bf16 v[52:55], v[124:127], v[206:209], v[32:35]
	v_mfma_f32_16x16x32_bf16 v[32:35], v[170:173], v[202:205], v[56:59]
	v_mfma_f32_16x16x32_bf16 v[190:193], v[174:177], v[206:209], v[32:35]
	s_setprio 0
	s_barrier
	s_mov_b32 m0, s75
	v_lshl_add_u64 v[246:247], s[46:47], 0, v[132:133]
	s_add_u32 s42, s46, 0x10000
	s_nop 1
	ds_read_b128 v[32:35], v157 offset:16384
	ds_read_b128 v[36:39], v157 offset:17408
	ds_read_b128 v[48:51], v157 offset:18432
	ds_read_b128 v[56:59], v157 offset:19456
	ds_read_b128 v[194:197], v157 offset:20480
	ds_read_b128 v[198:201], v157 offset:21504
	ds_read_b128 v[202:205], v157 offset:22528
	ds_read_b128 v[206:209], v157 offset:23552
	global_load_lds_dwordx4 v[246:247], off
	v_lshl_add_u64 v[248:249], s[46:47], 0, v[128:129]
	s_mov_b32 m0, s35
	s_addc_u32 s43, s47, 0
	global_load_lds_dwordx4 v[248:249], off
	v_lshl_add_u64 v[210:211], s[42:43], 0, v[132:133]
	s_mov_b32 m0, s41
	v_lshl_add_u64 v[250:251], s[48:49], 0, v[134:135]
	global_load_lds_dwordx4 v[210:211], off
	v_lshl_add_u64 v[210:211], s[42:43], 0, v[128:129]
	s_mov_b32 m0, s74
	v_lshl_add_u64 v[252:253], s[48:49], 0, v[130:131]
	global_load_lds_dwordx4 v[210:211], off
	s_mov_b32 m0, s60
	s_nop 0
	global_load_lds_dwordx4 v[250:251], off
	s_mov_b32 m0, s61
	s_nop 0
	global_load_lds_dwordx4 v[252:253], off
	s_waitcnt vmcnt(8)
	s_waitcnt lgkmcnt(0)
	s_barrier
	s_setprio 1
	s_waitcnt lgkmcnt(0)
	v_mfma_f32_16x16x32_bf16 v[0:3], v[104:107], v[202:205], v[0:3]
	v_mfma_f32_16x16x32_bf16 v[140:143], v[104:107], v[32:35], v[140:143]
	v_mfma_f32_16x16x32_bf16 v[148:151], v[104:107], v[48:51], v[148:151]
	v_mfma_f32_16x16x32_bf16 v[162:165], v[104:107], v[194:197], v[162:165]
	v_mfma_f32_16x16x32_bf16 v[104:107], v[108:111], v[206:209], v[0:3]
	v_mfma_f32_16x16x32_bf16 v[0:3], v[112:115], v[202:205], v[4:7]
	v_mfma_f32_16x16x32_bf16 v[140:143], v[108:111], v[36:39], v[140:143]
	v_mfma_f32_16x16x32_bf16 v[144:147], v[112:115], v[32:35], v[144:147]
	v_mfma_f32_16x16x32_bf16 v[148:151], v[108:111], v[56:59], v[148:151]
	v_mfma_f32_16x16x32_bf16 v[158:161], v[112:115], v[48:51], v[158:161]
	v_mfma_f32_16x16x32_bf16 v[162:165], v[108:111], v[198:201], v[162:165]
	v_mfma_f32_16x16x32_bf16 v[166:169], v[112:115], v[194:197], v[166:169]
	v_mfma_f32_16x16x32_bf16 v[108:111], v[116:119], v[206:209], v[0:3]
	v_mfma_f32_16x16x32_bf16 v[144:147], v[116:119], v[36:39], v[144:147]
	v_mfma_f32_16x16x32_bf16 v[158:161], v[116:119], v[56:59], v[158:161]
	v_mfma_f32_16x16x32_bf16 v[166:169], v[116:119], v[198:201], v[166:169]
	s_setprio 0
	s_setprio 1
	v_mfma_f32_16x16x32_bf16 v[0:3], v[120:123], v[32:35], v[8:11]
	v_mfma_f32_16x16x32_bf16 v[112:115], v[124:127], v[36:39], v[0:3]
	v_mfma_f32_16x16x32_bf16 v[0:3], v[170:173], v[32:35], v[12:15]
	v_mfma_f32_16x16x32_bf16 v[116:119], v[174:177], v[36:39], v[0:3]
	v_mfma_f32_16x16x32_bf16 v[0:3], v[120:123], v[48:51], v[24:27]
	v_mfma_f32_16x16x32_bf16 v[210:213], v[124:127], v[56:59], v[0:3]
	v_mfma_f32_16x16x32_bf16 v[0:3], v[170:173], v[48:51], v[28:31]
	v_mfma_f32_16x16x32_bf16 v[214:217], v[174:177], v[56:59], v[0:3]
	v_mfma_f32_16x16x32_bf16 v[0:3], v[120:123], v[194:197], v[60:63]
	v_mfma_f32_16x16x32_bf16 v[218:221], v[124:127], v[198:201], v[0:3]
	v_mfma_f32_16x16x32_bf16 v[0:3], v[170:173], v[194:197], v[100:103]
	v_mfma_f32_16x16x32_bf16 v[194:197], v[174:177], v[198:201], v[0:3]
	v_mfma_f32_16x16x32_bf16 v[0:3], v[120:123], v[202:205], v[16:19]
	v_mfma_f32_16x16x32_bf16 v[198:201], v[124:127], v[206:209], v[0:3]
	v_mfma_f32_16x16x32_bf16 v[0:3], v[170:173], v[202:205], v[20:23]
	v_mfma_f32_16x16x32_bf16 v[170:173], v[174:177], v[206:209], v[0:3]
	s_setprio 0
	s_barrier
	ds_read_b128 v[60:63], v136
	ds_read_b128 v[120:123], v136 offset:1024
	ds_read_b128 v[124:127], v136 offset:2048
	ds_read_b128 v[174:177], v136 offset:3072
	ds_read_b128 v[202:205], v226
	ds_read_b128 v[206:209], v226 offset:1024
	ds_read_b128 v[222:225], v226 offset:2048
	ds_read_b128 v[226:229], v226 offset:3072
	s_add_u32 s42, s48, 0x40000
	s_addc_u32 s43, s49, 0
	s_mov_b32 m0, s62
	v_lshl_add_u64 v[0:1], s[42:43], 0, v[134:135]
	ds_read_b128 v[24:27], v157 offset:32768
	ds_read_b128 v[28:31], v157 offset:33792
	ds_read_b128 v[56:59], v157 offset:34816
	ds_read_b128 v[100:103], v157 offset:35840
	ds_read_b128 v[230:233], v157 offset:36864
	ds_read_b128 v[234:237], v157 offset:37888
	ds_read_b128 v[238:241], v157 offset:38912
	ds_read_b128 v[242:245], v157 offset:39936
	global_load_lds_dwordx4 v[0:1], off
	v_lshl_add_u64 v[0:1], s[42:43], 0, v[130:131]
	s_mov_b32 m0, s63
	s_nop 0
	global_load_lds_dwordx4 v[0:1], off
	s_waitcnt vmcnt(8)
	s_waitcnt lgkmcnt(0)
	s_barrier
	s_setprio 1
	s_waitcnt lgkmcnt(0)
	v_mfma_f32_16x16x32_bf16 v[0:3], v[60:63], v[24:27], v[64:67]
	v_mfma_f32_16x16x32_bf16 v[32:35], v[120:123], v[28:31], v[0:3]
	v_mfma_f32_16x16x32_bf16 v[0:3], v[124:127], v[24:27], v[68:71]
	v_mfma_f32_16x16x32_bf16 v[36:39], v[174:177], v[28:31], v[0:3]
	v_mfma_f32_16x16x32_bf16 v[0:3], v[60:63], v[56:59], v[72:75]
	v_mfma_f32_16x16x32_bf16 v[16:19], v[120:123], v[100:103], v[0:3]
	v_mfma_f32_16x16x32_bf16 v[0:3], v[124:127], v[56:59], v[76:79]
	v_mfma_f32_16x16x32_bf16 v[20:23], v[174:177], v[100:103], v[0:3]
	v_mfma_f32_16x16x32_bf16 v[0:3], v[60:63], v[230:233], v[80:83]
	v_mfma_f32_16x16x32_bf16 v[8:11], v[120:123], v[234:237], v[0:3]
	v_mfma_f32_16x16x32_bf16 v[0:3], v[124:127], v[230:233], v[84:87]
	v_mfma_f32_16x16x32_bf16 v[12:15], v[174:177], v[234:237], v[0:3]
	v_mfma_f32_16x16x32_bf16 v[0:3], v[60:63], v[238:241], v[88:91]
	v_mfma_f32_16x16x32_bf16 v[4:7], v[124:127], v[238:241], v[92:95]
	v_mfma_f32_16x16x32_bf16 v[0:3], v[120:123], v[242:245], v[0:3]
	v_mfma_f32_16x16x32_bf16 v[4:7], v[174:177], v[242:245], v[4:7]
	s_setprio 0
	s_setprio 1
	v_mfma_f32_16x16x32_bf16 v[48:51], v[202:205], v[24:27], v[96:99]
	v_mfma_f32_16x16x32_bf16 v[24:27], v[222:225], v[24:27], v[178:181]
	v_mfma_f32_16x16x32_bf16 v[72:75], v[226:229], v[28:31], v[24:27]
	v_mfma_f32_16x16x32_bf16 v[24:27], v[202:205], v[56:59], v[182:185]
	v_mfma_f32_16x16x32_bf16 v[64:67], v[206:209], v[28:31], v[48:51]
	v_mfma_f32_16x16x32_bf16 v[48:51], v[206:209], v[100:103], v[24:27]
	v_mfma_f32_16x16x32_bf16 v[24:27], v[222:225], v[56:59], v[40:43]
	v_mfma_f32_16x16x32_bf16 v[56:59], v[226:229], v[100:103], v[24:27]
	v_mfma_f32_16x16x32_bf16 v[24:27], v[202:205], v[230:233], v[44:47]
	v_mfma_f32_16x16x32_bf16 v[40:43], v[206:209], v[234:237], v[24:27]
	v_mfma_f32_16x16x32_bf16 v[24:27], v[222:225], v[230:233], v[186:189]
	v_mfma_f32_16x16x32_bf16 v[44:47], v[226:229], v[234:237], v[24:27]
	v_mfma_f32_16x16x32_bf16 v[24:27], v[202:205], v[238:241], v[52:55]
	v_mfma_f32_16x16x32_bf16 v[28:31], v[222:225], v[238:241], v[190:193]
	v_mfma_f32_16x16x32_bf16 v[24:27], v[206:209], v[242:245], v[24:27]
	v_mfma_f32_16x16x32_bf16 v[28:31], v[226:229], v[242:245], v[28:31]
	s_setprio 0
	s_barrier
	s_mov_b32 m0, s78
	v_lshl_add_u64 v[52:53], v[246:247], 0, s[12:13]
	s_add_u32 s42, s46, 0x10080
	ds_read_b128 v[88:91], v157 offset:49152
	ds_read_b128 v[92:95], v157 offset:50176
	ds_read_b128 v[178:181], v157 offset:51200
	ds_read_b128 v[182:185], v157 offset:52224
	ds_read_b128 v[186:189], v157 offset:53248
	ds_read_b128 v[190:193], v157 offset:54272
	ds_read_b128 v[230:233], v157 offset:55296
	ds_read_b128 v[234:237], v157 offset:56320
	global_load_lds_dwordx4 v[52:53], off
	v_lshl_add_u64 v[52:53], v[248:249], 0, s[12:13]
	s_mov_b32 m0, s76
	s_addc_u32 s43, s47, 0
	global_load_lds_dwordx4 v[52:53], off
	v_lshl_add_u64 v[52:53], s[42:43], 0, v[132:133]
	s_mov_b32 m0, s44
	s_nop 0
	global_load_lds_dwordx4 v[52:53], off
	v_lshl_add_u64 v[52:53], s[42:43], 0, v[128:129]
	s_mov_b32 m0, s45
	s_nop 0
	global_load_lds_dwordx4 v[52:53], off
	v_lshl_add_u64 v[52:53], v[250:251], 0, s[12:13]
	s_mov_b32 m0, s64
	s_nop 0
	global_load_lds_dwordx4 v[52:53], off
	v_lshl_add_u64 v[52:53], v[252:253], 0, s[12:13]
	s_mov_b32 m0, s65
	s_nop 0
	global_load_lds_dwordx4 v[52:53], off
	s_waitcnt vmcnt(8)
	s_waitcnt lgkmcnt(0)
	s_barrier
	s_setprio 1
	s_waitcnt lgkmcnt(0)
	v_mfma_f32_16x16x32_bf16 v[52:55], v[60:63], v[88:91], v[140:143]
	v_mfma_f32_16x16x32_bf16 v[96:99], v[120:123], v[92:95], v[52:55]
	v_mfma_f32_16x16x32_bf16 v[52:55], v[124:127], v[88:91], v[144:147]
	v_mfma_f32_16x16x32_bf16 v[100:103], v[174:177], v[92:95], v[52:55]
	v_mfma_f32_16x16x32_bf16 v[52:55], v[60:63], v[178:181], v[148:151]
	v_mfma_f32_16x16x32_bf16 v[80:83], v[120:123], v[182:185], v[52:55]
	v_mfma_f32_16x16x32_bf16 v[52:55], v[124:127], v[178:181], v[158:161]
	v_mfma_f32_16x16x32_bf16 v[84:87], v[174:177], v[182:185], v[52:55]
	v_mfma_f32_16x16x32_bf16 v[52:55], v[60:63], v[186:189], v[162:165]
	v_mfma_f32_16x16x32_bf16 v[68:71], v[120:123], v[190:193], v[52:55]
	v_mfma_f32_16x16x32_bf16 v[52:55], v[124:127], v[186:189], v[166:169]
	v_mfma_f32_16x16x32_bf16 v[76:79], v[174:177], v[190:193], v[52:55]
	v_mfma_f32_16x16x32_bf16 v[52:55], v[60:63], v[230:233], v[104:107]
	v_mfma_f32_16x16x32_bf16 v[60:63], v[124:127], v[230:233], v[108:111]
	v_mfma_f32_16x16x32_bf16 v[52:55], v[120:123], v[234:237], v[52:55]
	v_mfma_f32_16x16x32_bf16 v[60:63], v[174:177], v[234:237], v[60:63]
	s_setprio 0
	s_setprio 1
	v_mfma_f32_16x16x32_bf16 v[104:107], v[202:205], v[88:91], v[112:115]
	v_mfma_f32_16x16x32_bf16 v[88:91], v[222:225], v[88:91], v[116:119]
	v_mfma_f32_16x16x32_bf16 v[124:127], v[226:229], v[92:95], v[88:91]
	v_mfma_f32_16x16x32_bf16 v[88:91], v[202:205], v[178:181], v[210:213]
	v_mfma_f32_16x16x32_bf16 v[112:115], v[206:209], v[182:185], v[88:91]
	v_mfma_f32_16x16x32_bf16 v[88:91], v[222:225], v[178:181], v[214:217]
	v_mfma_f32_16x16x32_bf16 v[116:119], v[226:229], v[182:185], v[88:91]
	v_mfma_f32_16x16x32_bf16 v[88:91], v[202:205], v[186:189], v[218:221]
	v_mfma_f32_16x16x32_bf16 v[120:123], v[206:209], v[92:95], v[104:107]
	v_mfma_f32_16x16x32_bf16 v[104:107], v[206:209], v[190:193], v[88:91]
	v_mfma_f32_16x16x32_bf16 v[88:91], v[222:225], v[186:189], v[194:197]
	v_mfma_f32_16x16x32_bf16 v[108:111], v[226:229], v[190:193], v[88:91]
	v_mfma_f32_16x16x32_bf16 v[88:91], v[202:205], v[230:233], v[198:201]
	v_mfma_f32_16x16x32_bf16 v[92:95], v[222:225], v[230:233], v[170:173]
	v_mfma_f32_16x16x32_bf16 v[88:91], v[206:209], v[234:237], v[88:91]
	v_mfma_f32_16x16x32_bf16 v[92:95], v[226:229], v[234:237], v[92:95]
	s_setprio 0
	s_barrier
	s_andn2_b64 vcc, exec, s[14:15]
	s_cbranch_vccnz .LBB0_620
	s_barrier

.LBB0_1363:
	ds_read_b128 v[144:147], v151
	ds_read_b128 v[154:157], v151 offset:1024
	ds_read_b128 v[158:161], v151 offset:2048
	ds_read_b128 v[162:165], v151 offset:3072
	ds_read_b128 v[166:169], v152
	ds_read_b128 v[170:173], v152 offset:1024
	ds_read_b128 v[174:177], v152 offset:2048
	ds_read_b128 v[178:181], v152 offset:3072
	s_add_u32 s34, s30, 0xfff00080
	s_addc_u32 s35, s31, -1
	s_cmp_eq_u32 s56, 60
	s_cselect_b32 s37, s0, s35
	s_cselect_b32 s36, s1, s34
	s_cselect_b32 s35, s19, s55
	s_cselect_b32 s34, s21, s27
	v_lshl_add_u64 v[214:215], s[30:31], 0, v[138:139]
	s_add_i32 m0, s29, 0xc000
	ds_read_b128 v[182:185], v153
	ds_read_b128 v[186:189], v153 offset:1024
	ds_read_b128 v[190:193], v153 offset:2048
	ds_read_b128 v[194:197], v153 offset:3072
	ds_read_b128 v[198:201], v153 offset:4096
	ds_read_b128 v[202:205], v153 offset:5120
	ds_read_b128 v[206:209], v153 offset:6144
	ds_read_b128 v[210:213], v153 offset:7168
	global_load_lds_dwordx4 v[214:215], off
	v_lshl_add_u64 v[214:215], s[30:31], 0, v[136:137]
	s_add_i32 m0, s29, 0xe000
	s_nop 0
	global_load_lds_dwordx4 v[214:215], off
	s_waitcnt vmcnt(8)
	s_waitcnt lgkmcnt(0)
	s_barrier
	s_setprio 1
	s_waitcnt lgkmcnt(0)
	v_mfma_f32_16x16x32_bf16 v[124:127], v[144:147], v[182:185], v[124:127]
	v_mfma_f32_16x16x32_bf16 v[120:123], v[158:161], v[182:185], v[120:123]
	v_mfma_f32_16x16x32_bf16 v[104:107], v[158:161], v[190:193], v[104:107]
	v_mfma_f32_16x16x32_bf16 v[108:111], v[144:147], v[190:193], v[108:111]
	v_mfma_f32_16x16x32_bf16 v[92:95], v[144:147], v[198:201], v[92:95]
	v_mfma_f32_16x16x32_bf16 v[88:91], v[158:161], v[198:201], v[88:91]
	v_mfma_f32_16x16x32_bf16 v[72:75], v[158:161], v[206:209], v[72:75]
	v_mfma_f32_16x16x32_bf16 v[76:79], v[144:147], v[206:209], v[76:79]
	v_mfma_f32_16x16x32_bf16 v[124:127], v[154:157], v[186:189], v[124:127]
	v_mfma_f32_16x16x32_bf16 v[120:123], v[162:165], v[186:189], v[120:123]
	v_mfma_f32_16x16x32_bf16 v[104:107], v[162:165], v[194:197], v[104:107]
	v_mfma_f32_16x16x32_bf16 v[108:111], v[154:157], v[194:197], v[108:111]
	v_mfma_f32_16x16x32_bf16 v[92:95], v[154:157], v[202:205], v[92:95]
	v_mfma_f32_16x16x32_bf16 v[88:91], v[162:165], v[202:205], v[88:91]
	v_mfma_f32_16x16x32_bf16 v[72:75], v[162:165], v[210:213], v[72:75]
	v_mfma_f32_16x16x32_bf16 v[76:79], v[154:157], v[210:213], v[76:79]
	s_setprio 0
	s_setprio 1
	v_mfma_f32_16x16x32_bf16 v[116:119], v[166:169], v[182:185], v[116:119]
	v_mfma_f32_16x16x32_bf16 v[112:115], v[174:177], v[182:185], v[112:115]
	v_mfma_f32_16x16x32_bf16 v[96:99], v[174:177], v[190:193], v[96:99]
	v_mfma_f32_16x16x32_bf16 v[100:103], v[166:169], v[190:193], v[100:103]
	v_mfma_f32_16x16x32_bf16 v[84:87], v[166:169], v[198:201], v[84:87]
	v_mfma_f32_16x16x32_bf16 v[80:83], v[174:177], v[198:201], v[80:83]
	v_mfma_f32_16x16x32_bf16 v[64:67], v[174:177], v[206:209], v[64:67]
	v_mfma_f32_16x16x32_bf16 v[68:71], v[166:169], v[206:209], v[68:71]
	v_mfma_f32_16x16x32_bf16 v[116:119], v[170:173], v[186:189], v[116:119]
	v_mfma_f32_16x16x32_bf16 v[112:115], v[178:181], v[186:189], v[112:115]
	v_mfma_f32_16x16x32_bf16 v[96:99], v[178:181], v[194:197], v[96:99]
	v_mfma_f32_16x16x32_bf16 v[100:103], v[170:173], v[194:197], v[100:103]
	v_mfma_f32_16x16x32_bf16 v[84:87], v[170:173], v[202:205], v[84:87]
	v_mfma_f32_16x16x32_bf16 v[80:83], v[178:181], v[202:205], v[80:83]
	v_mfma_f32_16x16x32_bf16 v[64:67], v[178:181], v[210:213], v[64:67]
	v_mfma_f32_16x16x32_bf16 v[68:71], v[170:173], v[210:213], v[68:71]
	s_setprio 0
	s_barrier
	s_add_i32 s57, s53, s44
	v_lshl_add_u64 v[214:215], s[34:35], 0, v[130:131]
	s_mov_b32 m0, s57
	ds_read_b128 v[182:185], v153 offset:16384
	ds_read_b128 v[186:189], v153 offset:17408
	ds_read_b128 v[190:193], v153 offset:18432
	ds_read_b128 v[194:197], v153 offset:19456
	ds_read_b128 v[198:201], v153 offset:20480
	ds_read_b128 v[202:205], v153 offset:21504
	ds_read_b128 v[206:209], v153 offset:22528
	ds_read_b128 v[210:213], v153 offset:23552
	global_load_lds_dwordx4 v[214:215], off
	s_add_i32 m0, s57, 0x2000
	s_add_u32 s58, s34, 0x100000
	v_lshl_add_u64 v[216:217], s[34:35], 0, v[134:135]
	s_addc_u32 s59, s35, 0
	s_add_i32 s57, s54, s44
	global_load_lds_dwordx4 v[216:217], off
	v_lshl_add_u64 v[218:219], s[58:59], 0, v[130:131]
	s_mov_b32 m0, s57
	v_lshl_add_u64 v[220:221], s[36:37], 0, v[132:133]
	global_load_lds_dwordx4 v[218:219], off
	v_lshl_add_u64 v[218:219], s[58:59], 0, v[134:135]
	s_add_i32 m0, s57, 0x2000
	s_nop 0
	global_load_lds_dwordx4 v[218:219], off
	v_lshl_add_u64 v[218:219], s[36:37], 0, v[128:129]
	s_mov_b32 m0, s29
	s_nop 0
	global_load_lds_dwordx4 v[218:219], off
	s_mov_b32 m0, s45
	s_nop 0
	global_load_lds_dwordx4 v[220:221], off
	s_waitcnt vmcnt(8)
	s_waitcnt lgkmcnt(0)
	s_barrier
	s_setprio 1
	s_waitcnt lgkmcnt(0)
	v_mfma_f32_16x16x32_bf16 v[60:63], v[144:147], v[182:185], v[60:63]
	v_mfma_f32_16x16x32_bf16 v[56:59], v[158:161], v[182:185], v[56:59]
	v_mfma_f32_16x16x32_bf16 v[40:43], v[158:161], v[190:193], v[40:43]
	v_mfma_f32_16x16x32_bf16 v[44:47], v[144:147], v[190:193], v[44:47]
	v_mfma_f32_16x16x32_bf16 v[28:31], v[144:147], v[198:201], v[28:31]
	v_mfma_f32_16x16x32_bf16 v[24:27], v[158:161], v[198:201], v[24:27]
	v_mfma_f32_16x16x32_bf16 v[8:11], v[158:161], v[206:209], v[8:11]
	v_mfma_f32_16x16x32_bf16 v[12:15], v[144:147], v[206:209], v[12:15]
	v_mfma_f32_16x16x32_bf16 v[60:63], v[154:157], v[186:189], v[60:63]
	v_mfma_f32_16x16x32_bf16 v[56:59], v[162:165], v[186:189], v[56:59]
	v_mfma_f32_16x16x32_bf16 v[40:43], v[162:165], v[194:197], v[40:43]
	v_mfma_f32_16x16x32_bf16 v[44:47], v[154:157], v[194:197], v[44:47]
	v_mfma_f32_16x16x32_bf16 v[28:31], v[154:157], v[202:205], v[28:31]
	v_mfma_f32_16x16x32_bf16 v[24:27], v[162:165], v[202:205], v[24:27]
	v_mfma_f32_16x16x32_bf16 v[8:11], v[162:165], v[210:213], v[8:11]
	v_mfma_f32_16x16x32_bf16 v[12:15], v[154:157], v[210:213], v[12:15]
	s_setprio 0
	s_setprio 1
	v_mfma_f32_16x16x32_bf16 v[52:55], v[166:169], v[182:185], v[52:55]
	v_mfma_f32_16x16x32_bf16 v[48:51], v[174:177], v[182:185], v[48:51]
	v_mfma_f32_16x16x32_bf16 v[32:35], v[174:177], v[190:193], v[32:35]
	v_mfma_f32_16x16x32_bf16 v[36:39], v[166:169], v[190:193], v[36:39]
	v_mfma_f32_16x16x32_bf16 v[20:23], v[166:169], v[198:201], v[20:23]
	v_mfma_f32_16x16x32_bf16 v[16:19], v[174:177], v[198:201], v[16:19]
	v_mfma_f32_16x16x32_bf16 v[0:3], v[174:177], v[206:209], v[0:3]
	v_mfma_f32_16x16x32_bf16 v[4:7], v[166:169], v[206:209], v[4:7]
	v_mfma_f32_16x16x32_bf16 v[52:55], v[170:173], v[186:189], v[52:55]
	v_mfma_f32_16x16x32_bf16 v[48:51], v[178:181], v[186:189], v[48:51]
	v_mfma_f32_16x16x32_bf16 v[32:35], v[178:181], v[194:197], v[32:35]
	v_mfma_f32_16x16x32_bf16 v[36:39], v[170:173], v[194:197], v[36:39]
	v_mfma_f32_16x16x32_bf16 v[20:23], v[170:173], v[202:205], v[20:23]
	v_mfma_f32_16x16x32_bf16 v[16:19], v[178:181], v[202:205], v[16:19]
	v_mfma_f32_16x16x32_bf16 v[0:3], v[178:181], v[210:213], v[0:3]
	v_mfma_f32_16x16x32_bf16 v[4:7], v[170:173], v[210:213], v[4:7]
	s_setprio 0
	s_barrier
	s_add_i32 s57, 0, 0x18000
	s_add_i32 s58, 0, 0x1c000
	v_add_u32_e32 v162, s57, v149
	v_add_u32_e32 v178, s58, v149
	ds_read_b128 v[144:147], v162
	ds_read_b128 v[154:157], v162 offset:1024
	ds_read_b128 v[158:161], v162 offset:2048
	ds_read_b128 v[162:165], v162 offset:3072
	ds_read_b128 v[166:169], v178
	ds_read_b128 v[170:173], v178 offset:1024
	ds_read_b128 v[174:177], v178 offset:2048
	ds_read_b128 v[178:181], v178 offset:3072
	s_add_u32 s36, s36, 0x100000
	s_addc_u32 s37, s37, 0
	s_mov_b32 m0, s46
	v_lshl_add_u64 v[222:223], s[36:37], 0, v[128:129]
	ds_read_b128 v[182:185], v153 offset:32768
	ds_read_b128 v[186:189], v153 offset:33792
	ds_read_b128 v[190:193], v153 offset:34816
	ds_read_b128 v[194:197], v153 offset:35840
	ds_read_b128 v[198:201], v153 offset:36864
	ds_read_b128 v[202:205], v153 offset:37888
	ds_read_b128 v[206:209], v153 offset:38912
	ds_read_b128 v[210:213], v153 offset:39936
	global_load_lds_dwordx4 v[222:223], off
	v_lshl_add_u64 v[222:223], s[36:37], 0, v[132:133]
	s_mov_b32 m0, s47
	s_nop 0
	global_load_lds_dwordx4 v[222:223], off
	s_waitcnt vmcnt(8)
	s_waitcnt lgkmcnt(0)
	s_barrier
	s_setprio 1
	s_waitcnt lgkmcnt(0)
	v_mfma_f32_16x16x32_bf16 v[124:127], v[144:147], v[182:185], v[124:127]
	v_mfma_f32_16x16x32_bf16 v[120:123], v[158:161], v[182:185], v[120:123]
	v_mfma_f32_16x16x32_bf16 v[104:107], v[158:161], v[190:193], v[104:107]
	v_mfma_f32_16x16x32_bf16 v[108:111], v[144:147], v[190:193], v[108:111]
	v_mfma_f32_16x16x32_bf16 v[92:95], v[144:147], v[198:201], v[92:95]
	v_mfma_f32_16x16x32_bf16 v[88:91], v[158:161], v[198:201], v[88:91]
	v_mfma_f32_16x16x32_bf16 v[72:75], v[158:161], v[206:209], v[72:75]
	v_mfma_f32_16x16x32_bf16 v[76:79], v[144:147], v[206:209], v[76:79]
	v_mfma_f32_16x16x32_bf16 v[124:127], v[154:157], v[186:189], v[124:127]
	v_mfma_f32_16x16x32_bf16 v[120:123], v[162:165], v[186:189], v[120:123]
	v_mfma_f32_16x16x32_bf16 v[104:107], v[162:165], v[194:197], v[104:107]
	v_mfma_f32_16x16x32_bf16 v[108:111], v[154:157], v[194:197], v[108:111]
	v_mfma_f32_16x16x32_bf16 v[92:95], v[154:157], v[202:205], v[92:95]
	v_mfma_f32_16x16x32_bf16 v[88:91], v[162:165], v[202:205], v[88:91]
	v_mfma_f32_16x16x32_bf16 v[72:75], v[162:165], v[210:213], v[72:75]
	v_mfma_f32_16x16x32_bf16 v[76:79], v[154:157], v[210:213], v[76:79]
	s_setprio 0
	s_setprio 1
	v_mfma_f32_16x16x32_bf16 v[116:119], v[166:169], v[182:185], v[116:119]
	v_mfma_f32_16x16x32_bf16 v[112:115], v[174:177], v[182:185], v[112:115]
	v_mfma_f32_16x16x32_bf16 v[96:99], v[174:177], v[190:193], v[96:99]
	v_mfma_f32_16x16x32_bf16 v[100:103], v[166:169], v[190:193], v[100:103]
	v_mfma_f32_16x16x32_bf16 v[84:87], v[166:169], v[198:201], v[84:87]
	v_mfma_f32_16x16x32_bf16 v[80:83], v[174:177], v[198:201], v[80:83]
	v_mfma_f32_16x16x32_bf16 v[64:67], v[174:177], v[206:209], v[64:67]
	v_mfma_f32_16x16x32_bf16 v[68:71], v[166:169], v[206:209], v[68:71]
	v_mfma_f32_16x16x32_bf16 v[116:119], v[170:173], v[186:189], v[116:119]
	v_mfma_f32_16x16x32_bf16 v[112:115], v[178:181], v[186:189], v[112:115]
	v_mfma_f32_16x16x32_bf16 v[96:99], v[178:181], v[194:197], v[96:99]
	v_mfma_f32_16x16x32_bf16 v[100:103], v[170:173], v[194:197], v[100:103]
	v_mfma_f32_16x16x32_bf16 v[84:87], v[170:173], v[202:205], v[84:87]
	v_mfma_f32_16x16x32_bf16 v[80:83], v[178:181], v[202:205], v[80:83]
	v_mfma_f32_16x16x32_bf16 v[64:67], v[178:181], v[210:213], v[64:67]
	v_mfma_f32_16x16x32_bf16 v[68:71], v[170:173], v[210:213], v[68:71]
	s_setprio 0
	s_barrier
	s_add_i32 s36, s57, s44
	v_lshl_add_u64 v[214:215], v[214:215], 0, s[14:15]
	s_mov_b32 m0, s36
	ds_read_b128 v[182:185], v153 offset:49152
	ds_read_b128 v[186:189], v153 offset:50176
	ds_read_b128 v[190:193], v153 offset:51200
	ds_read_b128 v[194:197], v153 offset:52224
	ds_read_b128 v[198:201], v153 offset:53248
	ds_read_b128 v[202:205], v153 offset:54272
	ds_read_b128 v[206:209], v153 offset:55296
	ds_read_b128 v[210:213], v153 offset:56320
	global_load_lds_dwordx4 v[214:215], off
	s_add_i32 m0, s36, 0x2000
	s_add_u32 s34, s34, 0x100080
	v_lshl_add_u64 v[214:215], v[216:217], 0, s[14:15]
	s_addc_u32 s35, s35, 0
	s_add_i32 s36, s58, s44
	global_load_lds_dwordx4 v[214:215], off
	v_lshl_add_u64 v[214:215], s[34:35], 0, v[130:131]
	s_mov_b32 m0, s36
	s_nop 0
	global_load_lds_dwordx4 v[214:215], off
	v_lshl_add_u64 v[214:215], s[34:35], 0, v[134:135]
	s_add_i32 m0, s36, 0x2000
	s_nop 0
	global_load_lds_dwordx4 v[214:215], off
	v_lshl_add_u64 v[214:215], v[218:219], 0, s[14:15]
	s_mov_b32 m0, s49
	s_nop 0
	global_load_lds_dwordx4 v[214:215], off
	v_lshl_add_u64 v[214:215], v[220:221], 0, s[14:15]
	s_mov_b32 m0, s50
	s_nop 0
	global_load_lds_dwordx4 v[214:215], off
	s_waitcnt vmcnt(8)
	s_waitcnt lgkmcnt(0)
	s_barrier
	s_setprio 1
	s_waitcnt lgkmcnt(0)
	v_mfma_f32_16x16x32_bf16 v[60:63], v[144:147], v[182:185], v[60:63]
	v_mfma_f32_16x16x32_bf16 v[56:59], v[158:161], v[182:185], v[56:59]
	v_mfma_f32_16x16x32_bf16 v[40:43], v[158:161], v[190:193], v[40:43]
	v_mfma_f32_16x16x32_bf16 v[44:47], v[144:147], v[190:193], v[44:47]
	v_mfma_f32_16x16x32_bf16 v[28:31], v[144:147], v[198:201], v[28:31]
	v_mfma_f32_16x16x32_bf16 v[24:27], v[158:161], v[198:201], v[24:27]
	v_mfma_f32_16x16x32_bf16 v[8:11], v[158:161], v[206:209], v[8:11]
	v_mfma_f32_16x16x32_bf16 v[12:15], v[144:147], v[206:209], v[12:15]
	v_mfma_f32_16x16x32_bf16 v[60:63], v[154:157], v[186:189], v[60:63]
	v_mfma_f32_16x16x32_bf16 v[56:59], v[162:165], v[186:189], v[56:59]
	v_mfma_f32_16x16x32_bf16 v[40:43], v[162:165], v[194:197], v[40:43]
	v_mfma_f32_16x16x32_bf16 v[44:47], v[154:157], v[194:197], v[44:47]
	v_mfma_f32_16x16x32_bf16 v[28:31], v[154:157], v[202:205], v[28:31]
	v_mfma_f32_16x16x32_bf16 v[24:27], v[162:165], v[202:205], v[24:27]
	v_mfma_f32_16x16x32_bf16 v[8:11], v[162:165], v[210:213], v[8:11]
	v_mfma_f32_16x16x32_bf16 v[12:15], v[154:157], v[210:213], v[12:15]
	s_setprio 0
	s_setprio 1
	v_mfma_f32_16x16x32_bf16 v[52:55], v[166:169], v[182:185], v[52:55]
	v_mfma_f32_16x16x32_bf16 v[48:51], v[174:177], v[182:185], v[48:51]
	v_mfma_f32_16x16x32_bf16 v[32:35], v[174:177], v[190:193], v[32:35]
	v_mfma_f32_16x16x32_bf16 v[36:39], v[166:169], v[190:193], v[36:39]
	v_mfma_f32_16x16x32_bf16 v[20:23], v[166:169], v[198:201], v[20:23]
	v_mfma_f32_16x16x32_bf16 v[16:19], v[174:177], v[198:201], v[16:19]
	v_mfma_f32_16x16x32_bf16 v[0:3], v[174:177], v[206:209], v[0:3]
	v_mfma_f32_16x16x32_bf16 v[4:7], v[166:169], v[206:209], v[4:7]
	v_mfma_f32_16x16x32_bf16 v[52:55], v[170:173], v[186:189], v[52:55]
	v_mfma_f32_16x16x32_bf16 v[48:51], v[178:181], v[186:189], v[48:51]
	v_mfma_f32_16x16x32_bf16 v[32:35], v[178:181], v[194:197], v[32:35]
	v_mfma_f32_16x16x32_bf16 v[36:39], v[170:173], v[194:197], v[36:39]
	v_mfma_f32_16x16x32_bf16 v[20:23], v[170:173], v[202:205], v[20:23]
	v_mfma_f32_16x16x32_bf16 v[16:19], v[178:181], v[202:205], v[16:19]
	v_mfma_f32_16x16x32_bf16 v[0:3], v[178:181], v[210:213], v[0:3]
	v_mfma_f32_16x16x32_bf16 v[4:7], v[170:173], v[210:213], v[4:7]
	s_setprio 0
	s_barrier
	s_add_i32 s56, s56, 2
	s_add_u32 s27, s27, 0x100
	s_addc_u32 s55, s55, 0
	s_add_u32 s30, s30, 0x100
	s_addc_u32 s31, s31, 0
	s_cmp_gt_u32 s56, 61
	s_cbranch_scc0 .LBB0_1363
	s_and_b64 vcc, exec, s[16:17]
	s_cbranch_vccz .LBB0_1366
	s_barrier

.LBB0_1461:
	ds_read_b128 v[144:147], v155
	ds_read_b128 v[148:151], v155 offset:1024
	ds_read_b128 v[160:163], v155 offset:2048
	ds_read_b128 v[164:167], v155 offset:3072
	ds_read_b128 v[168:171], v156
	ds_read_b128 v[172:175], v156 offset:1024
	ds_read_b128 v[176:179], v156 offset:2048
	ds_read_b128 v[180:183], v156 offset:3072
	s_add_u32 s38, s36, 0xfff00080
	s_addc_u32 s39, s37, -1
	s_cmp_eq_u32 s67, 60
	s_cselect_b32 s41, s1, s39
	s_cselect_b32 s40, s5, s38
	s_cselect_b32 s39, s27, s66
	s_cselect_b32 s38, s29, s65
	v_lshl_add_u64 v[216:217], s[36:37], 0, v[138:139]
	s_add_i32 m0, s50, 0xc000
	ds_read_b128 v[184:187], v157
	ds_read_b128 v[188:191], v157 offset:1024
	ds_read_b128 v[192:195], v157 offset:2048
	ds_read_b128 v[196:199], v157 offset:3072
	ds_read_b128 v[200:203], v157 offset:4096
	ds_read_b128 v[204:207], v157 offset:5120
	ds_read_b128 v[208:211], v157 offset:6144
	ds_read_b128 v[212:215], v157 offset:7168
	global_load_lds_dwordx4 v[216:217], off
	v_lshl_add_u64 v[216:217], s[36:37], 0, v[136:137]
	s_add_i32 m0, s50, 0xe000
	s_nop 0
	global_load_lds_dwordx4 v[216:217], off
	s_waitcnt vmcnt(8)
	s_waitcnt lgkmcnt(0)
	s_barrier
	s_setprio 1
	s_waitcnt lgkmcnt(0)
	v_mfma_f32_16x16x32_bf16 v[124:127], v[144:147], v[184:187], v[124:127]
	v_mfma_f32_16x16x32_bf16 v[120:123], v[160:163], v[184:187], v[120:123]
	v_mfma_f32_16x16x32_bf16 v[104:107], v[160:163], v[192:195], v[104:107]
	v_mfma_f32_16x16x32_bf16 v[108:111], v[144:147], v[192:195], v[108:111]
	v_mfma_f32_16x16x32_bf16 v[92:95], v[144:147], v[200:203], v[92:95]
	v_mfma_f32_16x16x32_bf16 v[88:91], v[160:163], v[200:203], v[88:91]
	v_mfma_f32_16x16x32_bf16 v[72:75], v[160:163], v[208:211], v[72:75]
	v_mfma_f32_16x16x32_bf16 v[76:79], v[144:147], v[208:211], v[76:79]
	v_mfma_f32_16x16x32_bf16 v[124:127], v[148:151], v[188:191], v[124:127]
	v_mfma_f32_16x16x32_bf16 v[120:123], v[164:167], v[188:191], v[120:123]
	v_mfma_f32_16x16x32_bf16 v[104:107], v[164:167], v[196:199], v[104:107]
	v_mfma_f32_16x16x32_bf16 v[108:111], v[148:151], v[196:199], v[108:111]
	v_mfma_f32_16x16x32_bf16 v[92:95], v[148:151], v[204:207], v[92:95]
	v_mfma_f32_16x16x32_bf16 v[88:91], v[164:167], v[204:207], v[88:91]
	v_mfma_f32_16x16x32_bf16 v[72:75], v[164:167], v[212:215], v[72:75]
	v_mfma_f32_16x16x32_bf16 v[76:79], v[148:151], v[212:215], v[76:79]
	s_setprio 0
	s_setprio 1
	v_mfma_f32_16x16x32_bf16 v[116:119], v[168:171], v[184:187], v[116:119]
	v_mfma_f32_16x16x32_bf16 v[112:115], v[176:179], v[184:187], v[112:115]
	v_mfma_f32_16x16x32_bf16 v[96:99], v[176:179], v[192:195], v[96:99]
	v_mfma_f32_16x16x32_bf16 v[100:103], v[168:171], v[192:195], v[100:103]
	v_mfma_f32_16x16x32_bf16 v[84:87], v[168:171], v[200:203], v[84:87]
	v_mfma_f32_16x16x32_bf16 v[80:83], v[176:179], v[200:203], v[80:83]
	v_mfma_f32_16x16x32_bf16 v[64:67], v[176:179], v[208:211], v[64:67]
	v_mfma_f32_16x16x32_bf16 v[68:71], v[168:171], v[208:211], v[68:71]
	v_mfma_f32_16x16x32_bf16 v[116:119], v[172:175], v[188:191], v[116:119]
	v_mfma_f32_16x16x32_bf16 v[112:115], v[180:183], v[188:191], v[112:115]
	v_mfma_f32_16x16x32_bf16 v[96:99], v[180:183], v[196:199], v[96:99]
	v_mfma_f32_16x16x32_bf16 v[100:103], v[172:175], v[196:199], v[100:103]
	v_mfma_f32_16x16x32_bf16 v[84:87], v[172:175], v[204:207], v[84:87]
	v_mfma_f32_16x16x32_bf16 v[80:83], v[180:183], v[204:207], v[80:83]
	v_mfma_f32_16x16x32_bf16 v[64:67], v[180:183], v[212:215], v[64:67]
	v_mfma_f32_16x16x32_bf16 v[68:71], v[172:175], v[212:215], v[68:71]
	s_setprio 0
	s_barrier
	s_add_i32 s68, s58, s49
	v_lshl_add_u64 v[216:217], s[38:39], 0, v[130:131]
	s_mov_b32 m0, s68
	ds_read_b128 v[184:187], v157 offset:16384
	ds_read_b128 v[188:191], v157 offset:17408
	ds_read_b128 v[192:195], v157 offset:18432
	ds_read_b128 v[196:199], v157 offset:19456
	ds_read_b128 v[200:203], v157 offset:20480
	ds_read_b128 v[204:207], v157 offset:21504
	ds_read_b128 v[208:211], v157 offset:22528
	ds_read_b128 v[212:215], v157 offset:23552
	global_load_lds_dwordx4 v[216:217], off
	s_add_i32 m0, s68, 0x2000
	s_add_u32 s68, s38, 0x100000
	v_lshl_add_u64 v[218:219], s[38:39], 0, v[134:135]
	s_addc_u32 s69, s39, 0
	s_add_i32 s70, s59, s49
	global_load_lds_dwordx4 v[218:219], off
	v_lshl_add_u64 v[220:221], s[68:69], 0, v[130:131]
	s_mov_b32 m0, s70
	v_lshl_add_u64 v[222:223], s[40:41], 0, v[132:133]
	global_load_lds_dwordx4 v[220:221], off
	v_lshl_add_u64 v[220:221], s[68:69], 0, v[134:135]
	s_add_i32 m0, s70, 0x2000
	s_nop 0
	global_load_lds_dwordx4 v[220:221], off
	v_lshl_add_u64 v[220:221], s[40:41], 0, v[128:129]
	s_mov_b32 m0, s50
	s_nop 0
	global_load_lds_dwordx4 v[220:221], off
	s_mov_b32 m0, s51
	s_nop 0
	global_load_lds_dwordx4 v[222:223], off
	s_waitcnt vmcnt(8)
	s_waitcnt lgkmcnt(0)
	s_barrier
	s_setprio 1
	s_waitcnt lgkmcnt(0)
	v_mfma_f32_16x16x32_bf16 v[60:63], v[144:147], v[184:187], v[60:63]
	v_mfma_f32_16x16x32_bf16 v[56:59], v[160:163], v[184:187], v[56:59]
	v_mfma_f32_16x16x32_bf16 v[40:43], v[160:163], v[192:195], v[40:43]
	v_mfma_f32_16x16x32_bf16 v[44:47], v[144:147], v[192:195], v[44:47]
	v_mfma_f32_16x16x32_bf16 v[28:31], v[144:147], v[200:203], v[28:31]
	v_mfma_f32_16x16x32_bf16 v[24:27], v[160:163], v[200:203], v[24:27]
	v_mfma_f32_16x16x32_bf16 v[8:11], v[160:163], v[208:211], v[8:11]
	v_mfma_f32_16x16x32_bf16 v[12:15], v[144:147], v[208:211], v[12:15]
	v_mfma_f32_16x16x32_bf16 v[60:63], v[148:151], v[188:191], v[60:63]
	v_mfma_f32_16x16x32_bf16 v[56:59], v[164:167], v[188:191], v[56:59]
	v_mfma_f32_16x16x32_bf16 v[40:43], v[164:167], v[196:199], v[40:43]
	v_mfma_f32_16x16x32_bf16 v[44:47], v[148:151], v[196:199], v[44:47]
	v_mfma_f32_16x16x32_bf16 v[28:31], v[148:151], v[204:207], v[28:31]
	v_mfma_f32_16x16x32_bf16 v[24:27], v[164:167], v[204:207], v[24:27]
	v_mfma_f32_16x16x32_bf16 v[8:11], v[164:167], v[212:215], v[8:11]
	v_mfma_f32_16x16x32_bf16 v[12:15], v[148:151], v[212:215], v[12:15]
	s_setprio 0
	s_setprio 1
	v_mfma_f32_16x16x32_bf16 v[52:55], v[168:171], v[184:187], v[52:55]
	v_mfma_f32_16x16x32_bf16 v[48:51], v[176:179], v[184:187], v[48:51]
	v_mfma_f32_16x16x32_bf16 v[32:35], v[176:179], v[192:195], v[32:35]
	v_mfma_f32_16x16x32_bf16 v[36:39], v[168:171], v[192:195], v[36:39]
	v_mfma_f32_16x16x32_bf16 v[20:23], v[168:171], v[200:203], v[20:23]
	v_mfma_f32_16x16x32_bf16 v[16:19], v[176:179], v[200:203], v[16:19]
	v_mfma_f32_16x16x32_bf16 v[0:3], v[176:179], v[208:211], v[0:3]
	v_mfma_f32_16x16x32_bf16 v[4:7], v[168:171], v[208:211], v[4:7]
	v_mfma_f32_16x16x32_bf16 v[52:55], v[172:175], v[188:191], v[52:55]
	v_mfma_f32_16x16x32_bf16 v[48:51], v[180:183], v[188:191], v[48:51]
	v_mfma_f32_16x16x32_bf16 v[32:35], v[180:183], v[196:199], v[32:35]
	v_mfma_f32_16x16x32_bf16 v[36:39], v[172:175], v[196:199], v[36:39]
	v_mfma_f32_16x16x32_bf16 v[20:23], v[172:175], v[204:207], v[20:23]
	v_mfma_f32_16x16x32_bf16 v[16:19], v[180:183], v[204:207], v[16:19]
	v_mfma_f32_16x16x32_bf16 v[0:3], v[180:183], v[212:215], v[0:3]
	v_mfma_f32_16x16x32_bf16 v[4:7], v[172:175], v[212:215], v[4:7]
	s_setprio 0
	s_barrier
	s_add_i32 s68, 0, 0x18000
	s_add_i32 s69, 0, 0x1c000
	v_add_u32_e32 v164, s68, v153
	v_add_u32_e32 v180, s69, v153
	ds_read_b128 v[144:147], v164
	ds_read_b128 v[148:151], v164 offset:1024
	ds_read_b128 v[160:163], v164 offset:2048
	ds_read_b128 v[164:167], v164 offset:3072
	ds_read_b128 v[168:171], v180
	ds_read_b128 v[172:175], v180 offset:1024
	ds_read_b128 v[176:179], v180 offset:2048
	ds_read_b128 v[180:183], v180 offset:3072
	s_add_u32 s40, s40, 0x100000
	s_addc_u32 s41, s41, 0
	s_mov_b32 m0, s52
	v_lshl_add_u64 v[224:225], s[40:41], 0, v[128:129]
	ds_read_b128 v[184:187], v157 offset:32768
	ds_read_b128 v[188:191], v157 offset:33792
	ds_read_b128 v[192:195], v157 offset:34816
	ds_read_b128 v[196:199], v157 offset:35840
	ds_read_b128 v[200:203], v157 offset:36864
	ds_read_b128 v[204:207], v157 offset:37888
	ds_read_b128 v[208:211], v157 offset:38912
	ds_read_b128 v[212:215], v157 offset:39936
	global_load_lds_dwordx4 v[224:225], off
	v_lshl_add_u64 v[224:225], s[40:41], 0, v[132:133]
	s_mov_b32 m0, s53
	s_nop 0
	global_load_lds_dwordx4 v[224:225], off
	s_waitcnt vmcnt(8)
	s_waitcnt lgkmcnt(0)
	s_barrier
	s_setprio 1
	s_waitcnt lgkmcnt(0)
	v_mfma_f32_16x16x32_bf16 v[124:127], v[144:147], v[184:187], v[124:127]
	v_mfma_f32_16x16x32_bf16 v[120:123], v[160:163], v[184:187], v[120:123]
	v_mfma_f32_16x16x32_bf16 v[104:107], v[160:163], v[192:195], v[104:107]
	v_mfma_f32_16x16x32_bf16 v[108:111], v[144:147], v[192:195], v[108:111]
	v_mfma_f32_16x16x32_bf16 v[92:95], v[144:147], v[200:203], v[92:95]
	v_mfma_f32_16x16x32_bf16 v[88:91], v[160:163], v[200:203], v[88:91]
	v_mfma_f32_16x16x32_bf16 v[72:75], v[160:163], v[208:211], v[72:75]
	v_mfma_f32_16x16x32_bf16 v[76:79], v[144:147], v[208:211], v[76:79]
	v_mfma_f32_16x16x32_bf16 v[124:127], v[148:151], v[188:191], v[124:127]
	v_mfma_f32_16x16x32_bf16 v[120:123], v[164:167], v[188:191], v[120:123]
	v_mfma_f32_16x16x32_bf16 v[104:107], v[164:167], v[196:199], v[104:107]
	v_mfma_f32_16x16x32_bf16 v[108:111], v[148:151], v[196:199], v[108:111]
	v_mfma_f32_16x16x32_bf16 v[92:95], v[148:151], v[204:207], v[92:95]
	v_mfma_f32_16x16x32_bf16 v[88:91], v[164:167], v[204:207], v[88:91]
	v_mfma_f32_16x16x32_bf16 v[72:75], v[164:167], v[212:215], v[72:75]
	v_mfma_f32_16x16x32_bf16 v[76:79], v[148:151], v[212:215], v[76:79]
	s_setprio 0
	s_setprio 1
	v_mfma_f32_16x16x32_bf16 v[116:119], v[168:171], v[184:187], v[116:119]
	v_mfma_f32_16x16x32_bf16 v[112:115], v[176:179], v[184:187], v[112:115]
	v_mfma_f32_16x16x32_bf16 v[96:99], v[176:179], v[192:195], v[96:99]
	v_mfma_f32_16x16x32_bf16 v[100:103], v[168:171], v[192:195], v[100:103]
	v_mfma_f32_16x16x32_bf16 v[84:87], v[168:171], v[200:203], v[84:87]
	v_mfma_f32_16x16x32_bf16 v[80:83], v[176:179], v[200:203], v[80:83]
	v_mfma_f32_16x16x32_bf16 v[64:67], v[176:179], v[208:211], v[64:67]
	v_mfma_f32_16x16x32_bf16 v[68:71], v[168:171], v[208:211], v[68:71]
	v_mfma_f32_16x16x32_bf16 v[116:119], v[172:175], v[188:191], v[116:119]
	v_mfma_f32_16x16x32_bf16 v[112:115], v[180:183], v[188:191], v[112:115]
	v_mfma_f32_16x16x32_bf16 v[96:99], v[180:183], v[196:199], v[96:99]
	v_mfma_f32_16x16x32_bf16 v[100:103], v[172:175], v[196:199], v[100:103]
	v_mfma_f32_16x16x32_bf16 v[84:87], v[172:175], v[204:207], v[84:87]
	v_mfma_f32_16x16x32_bf16 v[80:83], v[180:183], v[204:207], v[80:83]
	v_mfma_f32_16x16x32_bf16 v[64:67], v[180:183], v[212:215], v[64:67]
	v_mfma_f32_16x16x32_bf16 v[68:71], v[172:175], v[212:215], v[68:71]
	s_setprio 0
	s_barrier
	s_add_i32 s40, s68, s49
	v_lshl_add_u64 v[216:217], v[216:217], 0, s[14:15]
	s_mov_b32 m0, s40
	ds_read_b128 v[184:187], v157 offset:49152
	ds_read_b128 v[188:191], v157 offset:50176
	ds_read_b128 v[192:195], v157 offset:51200
	ds_read_b128 v[196:199], v157 offset:52224
	ds_read_b128 v[200:203], v157 offset:53248
	ds_read_b128 v[204:207], v157 offset:54272
	ds_read_b128 v[208:211], v157 offset:55296
	ds_read_b128 v[212:215], v157 offset:56320
	global_load_lds_dwordx4 v[216:217], off
	s_add_i32 m0, s40, 0x2000
	s_add_u32 s38, s38, 0x100080
	v_lshl_add_u64 v[216:217], v[218:219], 0, s[14:15]
	s_addc_u32 s39, s39, 0
	s_add_i32 s40, s69, s49
	global_load_lds_dwordx4 v[216:217], off
	v_lshl_add_u64 v[216:217], s[38:39], 0, v[130:131]
	s_mov_b32 m0, s40
	s_nop 0
	global_load_lds_dwordx4 v[216:217], off
	v_lshl_add_u64 v[216:217], s[38:39], 0, v[134:135]
	s_add_i32 m0, s40, 0x2000
	s_nop 0
	global_load_lds_dwordx4 v[216:217], off
	v_lshl_add_u64 v[216:217], v[220:221], 0, s[14:15]
	s_mov_b32 m0, s55
	s_nop 0
	global_load_lds_dwordx4 v[216:217], off
	v_lshl_add_u64 v[216:217], v[222:223], 0, s[14:15]
	s_mov_b32 m0, s56
	s_nop 0
	global_load_lds_dwordx4 v[216:217], off
	s_waitcnt vmcnt(8)
	s_waitcnt lgkmcnt(0)
	s_barrier
	s_setprio 1
	s_waitcnt lgkmcnt(0)
	v_mfma_f32_16x16x32_bf16 v[60:63], v[144:147], v[184:187], v[60:63]
	v_mfma_f32_16x16x32_bf16 v[56:59], v[160:163], v[184:187], v[56:59]
	v_mfma_f32_16x16x32_bf16 v[40:43], v[160:163], v[192:195], v[40:43]
	v_mfma_f32_16x16x32_bf16 v[44:47], v[144:147], v[192:195], v[44:47]
	v_mfma_f32_16x16x32_bf16 v[28:31], v[144:147], v[200:203], v[28:31]
	v_mfma_f32_16x16x32_bf16 v[24:27], v[160:163], v[200:203], v[24:27]
	v_mfma_f32_16x16x32_bf16 v[8:11], v[160:163], v[208:211], v[8:11]
	v_mfma_f32_16x16x32_bf16 v[12:15], v[144:147], v[208:211], v[12:15]
	v_mfma_f32_16x16x32_bf16 v[60:63], v[148:151], v[188:191], v[60:63]
	v_mfma_f32_16x16x32_bf16 v[56:59], v[164:167], v[188:191], v[56:59]
	v_mfma_f32_16x16x32_bf16 v[40:43], v[164:167], v[196:199], v[40:43]
	v_mfma_f32_16x16x32_bf16 v[44:47], v[148:151], v[196:199], v[44:47]
	v_mfma_f32_16x16x32_bf16 v[28:31], v[148:151], v[204:207], v[28:31]
	v_mfma_f32_16x16x32_bf16 v[24:27], v[164:167], v[204:207], v[24:27]
	v_mfma_f32_16x16x32_bf16 v[8:11], v[164:167], v[212:215], v[8:11]
	v_mfma_f32_16x16x32_bf16 v[12:15], v[148:151], v[212:215], v[12:15]
	s_setprio 0
	s_setprio 1
	v_mfma_f32_16x16x32_bf16 v[52:55], v[168:171], v[184:187], v[52:55]
	v_mfma_f32_16x16x32_bf16 v[48:51], v[176:179], v[184:187], v[48:51]
	v_mfma_f32_16x16x32_bf16 v[32:35], v[176:179], v[192:195], v[32:35]
	v_mfma_f32_16x16x32_bf16 v[36:39], v[168:171], v[192:195], v[36:39]
	v_mfma_f32_16x16x32_bf16 v[20:23], v[168:171], v[200:203], v[20:23]
	v_mfma_f32_16x16x32_bf16 v[16:19], v[176:179], v[200:203], v[16:19]
	v_mfma_f32_16x16x32_bf16 v[0:3], v[176:179], v[208:211], v[0:3]
	v_mfma_f32_16x16x32_bf16 v[4:7], v[168:171], v[208:211], v[4:7]
	v_mfma_f32_16x16x32_bf16 v[52:55], v[172:175], v[188:191], v[52:55]
	v_mfma_f32_16x16x32_bf16 v[48:51], v[180:183], v[188:191], v[48:51]
	v_mfma_f32_16x16x32_bf16 v[32:35], v[180:183], v[196:199], v[32:35]
	v_mfma_f32_16x16x32_bf16 v[36:39], v[172:175], v[196:199], v[36:39]
	v_mfma_f32_16x16x32_bf16 v[20:23], v[172:175], v[204:207], v[20:23]
	v_mfma_f32_16x16x32_bf16 v[16:19], v[180:183], v[204:207], v[16:19]
	v_mfma_f32_16x16x32_bf16 v[0:3], v[180:183], v[212:215], v[0:3]
	v_mfma_f32_16x16x32_bf16 v[4:7], v[172:175], v[212:215], v[4:7]
	s_setprio 0
	s_barrier
	s_add_i32 s67, s67, 2
	s_add_u32 s65, s65, 0x100
	s_addc_u32 s66, s66, 0
	s_add_u32 s36, s36, 0x100
	s_addc_u32 s37, s37, 0
	s_cmp_gt_u32 s67, 61
	s_cbranch_scc0 .LBB0_1461
	s_and_b64 vcc, exec, s[16:17]
	s_cbranch_vccz .LBB0_1464
	s_barrier

.LBB0_1539:
	ds_read_b128 v[144:147], v151
	ds_read_b128 v[154:157], v151 offset:1024
	ds_read_b128 v[158:161], v151 offset:2048
	ds_read_b128 v[162:165], v151 offset:3072
	ds_read_b128 v[166:169], v152
	ds_read_b128 v[170:173], v152 offset:1024
	ds_read_b128 v[174:177], v152 offset:2048
	ds_read_b128 v[178:181], v152 offset:3072
	s_add_u32 s34, s30, 0xffc00080
	s_addc_u32 s35, s31, -1
	s_cmpk_eq_i32 s56, 0xfc
	s_cselect_b32 s37, s0, s35
	s_cselect_b32 s36, s1, s34
	s_cselect_b32 s35, s19, s55
	s_cselect_b32 s34, s21, s27
	v_lshl_add_u64 v[214:215], s[30:31], 0, v[138:139]
	s_add_i32 m0, s29, 0xc000
	ds_read_b128 v[182:185], v153
	ds_read_b128 v[186:189], v153 offset:1024
	ds_read_b128 v[190:193], v153 offset:2048
	ds_read_b128 v[194:197], v153 offset:3072
	ds_read_b128 v[198:201], v153 offset:4096
	ds_read_b128 v[202:205], v153 offset:5120
	ds_read_b128 v[206:209], v153 offset:6144
	ds_read_b128 v[210:213], v153 offset:7168
	global_load_lds_dwordx4 v[214:215], off
	v_lshl_add_u64 v[214:215], s[30:31], 0, v[136:137]
	s_add_i32 m0, s29, 0xe000
	s_nop 0
	global_load_lds_dwordx4 v[214:215], off
	s_waitcnt vmcnt(8)
	s_waitcnt lgkmcnt(0)
	s_barrier
	s_setprio 1
	s_waitcnt lgkmcnt(0)
	v_mfma_f32_16x16x32_bf16 v[124:127], v[144:147], v[182:185], v[124:127]
	v_mfma_f32_16x16x32_bf16 v[120:123], v[158:161], v[182:185], v[120:123]
	v_mfma_f32_16x16x32_bf16 v[104:107], v[158:161], v[190:193], v[104:107]
	v_mfma_f32_16x16x32_bf16 v[108:111], v[144:147], v[190:193], v[108:111]
	v_mfma_f32_16x16x32_bf16 v[92:95], v[144:147], v[198:201], v[92:95]
	v_mfma_f32_16x16x32_bf16 v[88:91], v[158:161], v[198:201], v[88:91]
	v_mfma_f32_16x16x32_bf16 v[72:75], v[158:161], v[206:209], v[72:75]
	v_mfma_f32_16x16x32_bf16 v[76:79], v[144:147], v[206:209], v[76:79]
	v_mfma_f32_16x16x32_bf16 v[124:127], v[154:157], v[186:189], v[124:127]
	v_mfma_f32_16x16x32_bf16 v[120:123], v[162:165], v[186:189], v[120:123]
	v_mfma_f32_16x16x32_bf16 v[104:107], v[162:165], v[194:197], v[104:107]
	v_mfma_f32_16x16x32_bf16 v[108:111], v[154:157], v[194:197], v[108:111]
	v_mfma_f32_16x16x32_bf16 v[92:95], v[154:157], v[202:205], v[92:95]
	v_mfma_f32_16x16x32_bf16 v[88:91], v[162:165], v[202:205], v[88:91]
	v_mfma_f32_16x16x32_bf16 v[72:75], v[162:165], v[210:213], v[72:75]
	v_mfma_f32_16x16x32_bf16 v[76:79], v[154:157], v[210:213], v[76:79]
	s_setprio 0
	s_setprio 1
	v_mfma_f32_16x16x32_bf16 v[116:119], v[166:169], v[182:185], v[116:119]
	v_mfma_f32_16x16x32_bf16 v[112:115], v[174:177], v[182:185], v[112:115]
	v_mfma_f32_16x16x32_bf16 v[96:99], v[174:177], v[190:193], v[96:99]
	v_mfma_f32_16x16x32_bf16 v[100:103], v[166:169], v[190:193], v[100:103]
	v_mfma_f32_16x16x32_bf16 v[84:87], v[166:169], v[198:201], v[84:87]
	v_mfma_f32_16x16x32_bf16 v[80:83], v[174:177], v[198:201], v[80:83]
	v_mfma_f32_16x16x32_bf16 v[64:67], v[174:177], v[206:209], v[64:67]
	v_mfma_f32_16x16x32_bf16 v[68:71], v[166:169], v[206:209], v[68:71]
	v_mfma_f32_16x16x32_bf16 v[116:119], v[170:173], v[186:189], v[116:119]
	v_mfma_f32_16x16x32_bf16 v[112:115], v[178:181], v[186:189], v[112:115]
	v_mfma_f32_16x16x32_bf16 v[96:99], v[178:181], v[194:197], v[96:99]
	v_mfma_f32_16x16x32_bf16 v[100:103], v[170:173], v[194:197], v[100:103]
	v_mfma_f32_16x16x32_bf16 v[84:87], v[170:173], v[202:205], v[84:87]
	v_mfma_f32_16x16x32_bf16 v[80:83], v[178:181], v[202:205], v[80:83]
	v_mfma_f32_16x16x32_bf16 v[64:67], v[178:181], v[210:213], v[64:67]
	v_mfma_f32_16x16x32_bf16 v[68:71], v[170:173], v[210:213], v[68:71]
	s_setprio 0
	s_barrier
	s_add_i32 s57, s53, s44
	v_lshl_add_u64 v[214:215], s[34:35], 0, v[130:131]
	s_mov_b32 m0, s57
	ds_read_b128 v[182:185], v153 offset:16384
	ds_read_b128 v[186:189], v153 offset:17408
	ds_read_b128 v[190:193], v153 offset:18432
	ds_read_b128 v[194:197], v153 offset:19456
	ds_read_b128 v[198:201], v153 offset:20480
	ds_read_b128 v[202:205], v153 offset:21504
	ds_read_b128 v[206:209], v153 offset:22528
	ds_read_b128 v[210:213], v153 offset:23552
	global_load_lds_dwordx4 v[214:215], off
	s_add_i32 m0, s57, 0x2000
	s_add_u32 s58, s34, 0x400000
	v_lshl_add_u64 v[216:217], s[34:35], 0, v[134:135]
	s_addc_u32 s59, s35, 0
	s_add_i32 s57, s54, s44
	global_load_lds_dwordx4 v[216:217], off
	v_lshl_add_u64 v[218:219], s[58:59], 0, v[130:131]
	s_mov_b32 m0, s57
	v_lshl_add_u64 v[220:221], s[36:37], 0, v[132:133]
	global_load_lds_dwordx4 v[218:219], off
	v_lshl_add_u64 v[218:219], s[58:59], 0, v[134:135]
	s_add_i32 m0, s57, 0x2000
	s_nop 0
	global_load_lds_dwordx4 v[218:219], off
	v_lshl_add_u64 v[218:219], s[36:37], 0, v[128:129]
	s_mov_b32 m0, s29
	s_nop 0
	global_load_lds_dwordx4 v[218:219], off
	s_mov_b32 m0, s45
	s_nop 0
	global_load_lds_dwordx4 v[220:221], off
	s_waitcnt vmcnt(8)
	s_waitcnt lgkmcnt(0)
	s_barrier
	s_setprio 1
	s_waitcnt lgkmcnt(0)
	v_mfma_f32_16x16x32_bf16 v[60:63], v[144:147], v[182:185], v[60:63]
	v_mfma_f32_16x16x32_bf16 v[56:59], v[158:161], v[182:185], v[56:59]
	v_mfma_f32_16x16x32_bf16 v[40:43], v[158:161], v[190:193], v[40:43]
	v_mfma_f32_16x16x32_bf16 v[44:47], v[144:147], v[190:193], v[44:47]
	v_mfma_f32_16x16x32_bf16 v[28:31], v[144:147], v[198:201], v[28:31]
	v_mfma_f32_16x16x32_bf16 v[24:27], v[158:161], v[198:201], v[24:27]
	v_mfma_f32_16x16x32_bf16 v[8:11], v[158:161], v[206:209], v[8:11]
	v_mfma_f32_16x16x32_bf16 v[12:15], v[144:147], v[206:209], v[12:15]
	v_mfma_f32_16x16x32_bf16 v[60:63], v[154:157], v[186:189], v[60:63]
	v_mfma_f32_16x16x32_bf16 v[56:59], v[162:165], v[186:189], v[56:59]
	v_mfma_f32_16x16x32_bf16 v[40:43], v[162:165], v[194:197], v[40:43]
	v_mfma_f32_16x16x32_bf16 v[44:47], v[154:157], v[194:197], v[44:47]
	v_mfma_f32_16x16x32_bf16 v[28:31], v[154:157], v[202:205], v[28:31]
	v_mfma_f32_16x16x32_bf16 v[24:27], v[162:165], v[202:205], v[24:27]
	v_mfma_f32_16x16x32_bf16 v[8:11], v[162:165], v[210:213], v[8:11]
	v_mfma_f32_16x16x32_bf16 v[12:15], v[154:157], v[210:213], v[12:15]
	s_setprio 0
	s_setprio 1
	v_mfma_f32_16x16x32_bf16 v[52:55], v[166:169], v[182:185], v[52:55]
	v_mfma_f32_16x16x32_bf16 v[48:51], v[174:177], v[182:185], v[48:51]
	v_mfma_f32_16x16x32_bf16 v[32:35], v[174:177], v[190:193], v[32:35]
	v_mfma_f32_16x16x32_bf16 v[36:39], v[166:169], v[190:193], v[36:39]
	v_mfma_f32_16x16x32_bf16 v[20:23], v[166:169], v[198:201], v[20:23]
	v_mfma_f32_16x16x32_bf16 v[16:19], v[174:177], v[198:201], v[16:19]
	v_mfma_f32_16x16x32_bf16 v[0:3], v[174:177], v[206:209], v[0:3]
	v_mfma_f32_16x16x32_bf16 v[4:7], v[166:169], v[206:209], v[4:7]
	v_mfma_f32_16x16x32_bf16 v[52:55], v[170:173], v[186:189], v[52:55]
	v_mfma_f32_16x16x32_bf16 v[48:51], v[178:181], v[186:189], v[48:51]
	v_mfma_f32_16x16x32_bf16 v[32:35], v[178:181], v[194:197], v[32:35]
	v_mfma_f32_16x16x32_bf16 v[36:39], v[170:173], v[194:197], v[36:39]
	v_mfma_f32_16x16x32_bf16 v[20:23], v[170:173], v[202:205], v[20:23]
	v_mfma_f32_16x16x32_bf16 v[16:19], v[178:181], v[202:205], v[16:19]
	v_mfma_f32_16x16x32_bf16 v[0:3], v[178:181], v[210:213], v[0:3]
	v_mfma_f32_16x16x32_bf16 v[4:7], v[170:173], v[210:213], v[4:7]
	s_setprio 0
	s_barrier
	s_add_i32 s57, 0, 0x18000
	s_add_i32 s58, 0, 0x1c000
	v_add_u32_e32 v162, s57, v149
	v_add_u32_e32 v178, s58, v149
	ds_read_b128 v[144:147], v162
	ds_read_b128 v[154:157], v162 offset:1024
	ds_read_b128 v[158:161], v162 offset:2048
	ds_read_b128 v[162:165], v162 offset:3072
	ds_read_b128 v[166:169], v178
	ds_read_b128 v[170:173], v178 offset:1024
	ds_read_b128 v[174:177], v178 offset:2048
	ds_read_b128 v[178:181], v178 offset:3072
	s_add_u32 s36, s36, 0x400000
	s_addc_u32 s37, s37, 0
	s_mov_b32 m0, s46
	v_lshl_add_u64 v[222:223], s[36:37], 0, v[128:129]
	ds_read_b128 v[182:185], v153 offset:32768
	ds_read_b128 v[186:189], v153 offset:33792
	ds_read_b128 v[190:193], v153 offset:34816
	ds_read_b128 v[194:197], v153 offset:35840
	ds_read_b128 v[198:201], v153 offset:36864
	ds_read_b128 v[202:205], v153 offset:37888
	ds_read_b128 v[206:209], v153 offset:38912
	ds_read_b128 v[210:213], v153 offset:39936
	global_load_lds_dwordx4 v[222:223], off
	v_lshl_add_u64 v[222:223], s[36:37], 0, v[132:133]
	s_mov_b32 m0, s47
	s_nop 0
	global_load_lds_dwordx4 v[222:223], off
	s_waitcnt vmcnt(8)
	s_waitcnt lgkmcnt(0)
	s_barrier
	s_setprio 1
	s_waitcnt lgkmcnt(0)
	v_mfma_f32_16x16x32_bf16 v[124:127], v[144:147], v[182:185], v[124:127]
	v_mfma_f32_16x16x32_bf16 v[120:123], v[158:161], v[182:185], v[120:123]
	v_mfma_f32_16x16x32_bf16 v[104:107], v[158:161], v[190:193], v[104:107]
	v_mfma_f32_16x16x32_bf16 v[108:111], v[144:147], v[190:193], v[108:111]
	v_mfma_f32_16x16x32_bf16 v[92:95], v[144:147], v[198:201], v[92:95]
	v_mfma_f32_16x16x32_bf16 v[88:91], v[158:161], v[198:201], v[88:91]
	v_mfma_f32_16x16x32_bf16 v[72:75], v[158:161], v[206:209], v[72:75]
	v_mfma_f32_16x16x32_bf16 v[76:79], v[144:147], v[206:209], v[76:79]
	v_mfma_f32_16x16x32_bf16 v[124:127], v[154:157], v[186:189], v[124:127]
	v_mfma_f32_16x16x32_bf16 v[120:123], v[162:165], v[186:189], v[120:123]
	v_mfma_f32_16x16x32_bf16 v[104:107], v[162:165], v[194:197], v[104:107]
	v_mfma_f32_16x16x32_bf16 v[108:111], v[154:157], v[194:197], v[108:111]
	v_mfma_f32_16x16x32_bf16 v[92:95], v[154:157], v[202:205], v[92:95]
	v_mfma_f32_16x16x32_bf16 v[88:91], v[162:165], v[202:205], v[88:91]
	v_mfma_f32_16x16x32_bf16 v[72:75], v[162:165], v[210:213], v[72:75]
	v_mfma_f32_16x16x32_bf16 v[76:79], v[154:157], v[210:213], v[76:79]
	s_setprio 0
	s_setprio 1
	v_mfma_f32_16x16x32_bf16 v[116:119], v[166:169], v[182:185], v[116:119]
	v_mfma_f32_16x16x32_bf16 v[112:115], v[174:177], v[182:185], v[112:115]
	v_mfma_f32_16x16x32_bf16 v[96:99], v[174:177], v[190:193], v[96:99]
	v_mfma_f32_16x16x32_bf16 v[100:103], v[166:169], v[190:193], v[100:103]
	v_mfma_f32_16x16x32_bf16 v[84:87], v[166:169], v[198:201], v[84:87]
	v_mfma_f32_16x16x32_bf16 v[80:83], v[174:177], v[198:201], v[80:83]
	v_mfma_f32_16x16x32_bf16 v[64:67], v[174:177], v[206:209], v[64:67]
	v_mfma_f32_16x16x32_bf16 v[68:71], v[166:169], v[206:209], v[68:71]
	v_mfma_f32_16x16x32_bf16 v[116:119], v[170:173], v[186:189], v[116:119]
	v_mfma_f32_16x16x32_bf16 v[112:115], v[178:181], v[186:189], v[112:115]
	v_mfma_f32_16x16x32_bf16 v[96:99], v[178:181], v[194:197], v[96:99]
	v_mfma_f32_16x16x32_bf16 v[100:103], v[170:173], v[194:197], v[100:103]
	v_mfma_f32_16x16x32_bf16 v[84:87], v[170:173], v[202:205], v[84:87]
	v_mfma_f32_16x16x32_bf16 v[80:83], v[178:181], v[202:205], v[80:83]
	v_mfma_f32_16x16x32_bf16 v[64:67], v[178:181], v[210:213], v[64:67]
	v_mfma_f32_16x16x32_bf16 v[68:71], v[170:173], v[210:213], v[68:71]
	s_setprio 0
	s_barrier
	s_add_i32 s36, s57, s44
	v_lshl_add_u64 v[214:215], v[214:215], 0, s[14:15]
	s_mov_b32 m0, s36
	ds_read_b128 v[182:185], v153 offset:49152
	ds_read_b128 v[186:189], v153 offset:50176
	ds_read_b128 v[190:193], v153 offset:51200
	ds_read_b128 v[194:197], v153 offset:52224
	ds_read_b128 v[198:201], v153 offset:53248
	ds_read_b128 v[202:205], v153 offset:54272
	ds_read_b128 v[206:209], v153 offset:55296
	ds_read_b128 v[210:213], v153 offset:56320
	global_load_lds_dwordx4 v[214:215], off
	s_add_i32 m0, s36, 0x2000
	s_add_u32 s34, s34, 0x400080
	v_lshl_add_u64 v[214:215], v[216:217], 0, s[14:15]
	s_addc_u32 s35, s35, 0
	s_add_i32 s36, s58, s44
	global_load_lds_dwordx4 v[214:215], off
	v_lshl_add_u64 v[214:215], s[34:35], 0, v[130:131]
	s_mov_b32 m0, s36
	s_nop 0
	global_load_lds_dwordx4 v[214:215], off
	v_lshl_add_u64 v[214:215], s[34:35], 0, v[134:135]
	s_add_i32 m0, s36, 0x2000
	s_nop 0
	global_load_lds_dwordx4 v[214:215], off
	v_lshl_add_u64 v[214:215], v[218:219], 0, s[14:15]
	s_mov_b32 m0, s49
	s_nop 0
	global_load_lds_dwordx4 v[214:215], off
	v_lshl_add_u64 v[214:215], v[220:221], 0, s[14:15]
	s_mov_b32 m0, s50
	s_nop 0
	global_load_lds_dwordx4 v[214:215], off
	s_waitcnt vmcnt(8)
	s_waitcnt lgkmcnt(0)
	s_barrier
	s_setprio 1
	s_waitcnt lgkmcnt(0)
	v_mfma_f32_16x16x32_bf16 v[60:63], v[144:147], v[182:185], v[60:63]
	v_mfma_f32_16x16x32_bf16 v[56:59], v[158:161], v[182:185], v[56:59]
	v_mfma_f32_16x16x32_bf16 v[40:43], v[158:161], v[190:193], v[40:43]
	v_mfma_f32_16x16x32_bf16 v[44:47], v[144:147], v[190:193], v[44:47]
	v_mfma_f32_16x16x32_bf16 v[28:31], v[144:147], v[198:201], v[28:31]
	v_mfma_f32_16x16x32_bf16 v[24:27], v[158:161], v[198:201], v[24:27]
	v_mfma_f32_16x16x32_bf16 v[8:11], v[158:161], v[206:209], v[8:11]
	v_mfma_f32_16x16x32_bf16 v[12:15], v[144:147], v[206:209], v[12:15]
	v_mfma_f32_16x16x32_bf16 v[60:63], v[154:157], v[186:189], v[60:63]
	v_mfma_f32_16x16x32_bf16 v[56:59], v[162:165], v[186:189], v[56:59]
	v_mfma_f32_16x16x32_bf16 v[40:43], v[162:165], v[194:197], v[40:43]
	v_mfma_f32_16x16x32_bf16 v[44:47], v[154:157], v[194:197], v[44:47]
	v_mfma_f32_16x16x32_bf16 v[28:31], v[154:157], v[202:205], v[28:31]
	v_mfma_f32_16x16x32_bf16 v[24:27], v[162:165], v[202:205], v[24:27]
	v_mfma_f32_16x16x32_bf16 v[8:11], v[162:165], v[210:213], v[8:11]
	v_mfma_f32_16x16x32_bf16 v[12:15], v[154:157], v[210:213], v[12:15]
	s_setprio 0
	s_setprio 1
	v_mfma_f32_16x16x32_bf16 v[52:55], v[166:169], v[182:185], v[52:55]
	v_mfma_f32_16x16x32_bf16 v[48:51], v[174:177], v[182:185], v[48:51]
	v_mfma_f32_16x16x32_bf16 v[32:35], v[174:177], v[190:193], v[32:35]
	v_mfma_f32_16x16x32_bf16 v[36:39], v[166:169], v[190:193], v[36:39]
	v_mfma_f32_16x16x32_bf16 v[20:23], v[166:169], v[198:201], v[20:23]
	v_mfma_f32_16x16x32_bf16 v[16:19], v[174:177], v[198:201], v[16:19]
	v_mfma_f32_16x16x32_bf16 v[0:3], v[174:177], v[206:209], v[0:3]
	v_mfma_f32_16x16x32_bf16 v[4:7], v[166:169], v[206:209], v[4:7]
	v_mfma_f32_16x16x32_bf16 v[52:55], v[170:173], v[186:189], v[52:55]
	v_mfma_f32_16x16x32_bf16 v[48:51], v[178:181], v[186:189], v[48:51]
	v_mfma_f32_16x16x32_bf16 v[32:35], v[178:181], v[194:197], v[32:35]
	v_mfma_f32_16x16x32_bf16 v[36:39], v[170:173], v[194:197], v[36:39]
	v_mfma_f32_16x16x32_bf16 v[20:23], v[170:173], v[202:205], v[20:23]
	v_mfma_f32_16x16x32_bf16 v[16:19], v[178:181], v[202:205], v[16:19]
	v_mfma_f32_16x16x32_bf16 v[0:3], v[178:181], v[210:213], v[0:3]
	v_mfma_f32_16x16x32_bf16 v[4:7], v[170:173], v[210:213], v[4:7]
	s_setprio 0
	s_barrier
	s_add_i32 s56, s56, 2
	s_add_u32 s27, s27, 0x100
	s_addc_u32 s55, s55, 0
	s_add_u32 s30, s30, 0x100
	s_addc_u32 s31, s31, 0
	s_cmpk_gt_u32 s56, 0xfd
	s_cbranch_scc0 .LBB0_1539
	s_and_b64 vcc, exec, s[16:17]
	s_cbranch_vccz .LBB0_1542
	s_barrier

.LBB0_1945:
	ds_read_b128 v[146:149], v143
	ds_read_b128 v[150:153], v143 offset:1024
	ds_read_b128 v[154:157], v143 offset:2048
	ds_read_b128 v[158:161], v143 offset:3072
	ds_read_b128 v[162:165], v144
	ds_read_b128 v[166:169], v144 offset:1024
	ds_read_b128 v[170:173], v144 offset:2048
	ds_read_b128 v[174:177], v144 offset:3072
	s_add_u32 s38, s36, 0xfff00080
	s_addc_u32 s39, s37, -1
	s_cmp_eq_u32 s61, 4
	s_cselect_b32 s41, s5, s39
	s_cselect_b32 s40, s4, s38
	s_cselect_b32 s39, s29, s60
	s_cselect_b32 s38, s31, s59
	v_lshl_add_u64 v[210:211], s[36:37], 0, v[134:135]
	s_add_i32 m0, s17, 0xc000
	ds_read_b128 v[178:181], v145
	ds_read_b128 v[182:185], v145 offset:1024
	ds_read_b128 v[186:189], v145 offset:2048
	ds_read_b128 v[190:193], v145 offset:3072
	ds_read_b128 v[194:197], v145 offset:4096
	ds_read_b128 v[198:201], v145 offset:5120
	ds_read_b128 v[202:205], v145 offset:6144
	ds_read_b128 v[206:209], v145 offset:7168
	global_load_lds_dwordx4 v[210:211], off
	v_lshl_add_u64 v[210:211], s[36:37], 0, v[132:133]
	s_add_i32 m0, s17, 0xe000
	s_nop 0
	global_load_lds_dwordx4 v[210:211], off
	s_waitcnt vmcnt(8)
	s_waitcnt lgkmcnt(0)
	s_barrier
	s_setprio 1
	s_waitcnt lgkmcnt(0)
	v_mfma_f32_16x16x32_bf16 v[124:127], v[146:149], v[178:181], v[124:127]
	v_mfma_f32_16x16x32_bf16 v[120:123], v[154:157], v[178:181], v[120:123]
	v_mfma_f32_16x16x32_bf16 v[112:115], v[154:157], v[186:189], v[112:115]
	v_mfma_f32_16x16x32_bf16 v[116:119], v[146:149], v[186:189], v[116:119]
	v_mfma_f32_16x16x32_bf16 v[100:103], v[146:149], v[194:197], v[100:103]
	v_mfma_f32_16x16x32_bf16 v[96:99], v[154:157], v[194:197], v[96:99]
	v_mfma_f32_16x16x32_bf16 v[80:83], v[154:157], v[202:205], v[80:83]
	v_mfma_f32_16x16x32_bf16 v[84:87], v[146:149], v[202:205], v[84:87]
	v_mfma_f32_16x16x32_bf16 v[124:127], v[150:153], v[182:185], v[124:127]
	v_mfma_f32_16x16x32_bf16 v[120:123], v[158:161], v[182:185], v[120:123]
	v_mfma_f32_16x16x32_bf16 v[112:115], v[158:161], v[190:193], v[112:115]
	v_mfma_f32_16x16x32_bf16 v[116:119], v[150:153], v[190:193], v[116:119]
	v_mfma_f32_16x16x32_bf16 v[100:103], v[150:153], v[198:201], v[100:103]
	v_mfma_f32_16x16x32_bf16 v[96:99], v[158:161], v[198:201], v[96:99]
	v_mfma_f32_16x16x32_bf16 v[80:83], v[158:161], v[206:209], v[80:83]
	v_mfma_f32_16x16x32_bf16 v[84:87], v[150:153], v[206:209], v[84:87]
	s_setprio 0
	s_setprio 1
	v_mfma_f32_16x16x32_bf16 v[108:111], v[162:165], v[178:181], v[108:111]
	v_mfma_f32_16x16x32_bf16 v[104:107], v[170:173], v[178:181], v[104:107]
	v_mfma_f32_16x16x32_bf16 v[88:91], v[170:173], v[186:189], v[88:91]
	v_mfma_f32_16x16x32_bf16 v[92:95], v[162:165], v[186:189], v[92:95]
	v_mfma_f32_16x16x32_bf16 v[76:79], v[162:165], v[194:197], v[76:79]
	v_mfma_f32_16x16x32_bf16 v[72:75], v[170:173], v[194:197], v[72:75]
	v_mfma_f32_16x16x32_bf16 v[64:67], v[170:173], v[202:205], v[64:67]
	v_mfma_f32_16x16x32_bf16 v[68:71], v[162:165], v[202:205], v[68:71]
	v_mfma_f32_16x16x32_bf16 v[108:111], v[166:169], v[182:185], v[108:111]
	v_mfma_f32_16x16x32_bf16 v[104:107], v[174:177], v[182:185], v[104:107]
	v_mfma_f32_16x16x32_bf16 v[88:91], v[174:177], v[190:193], v[88:91]
	v_mfma_f32_16x16x32_bf16 v[92:95], v[166:169], v[190:193], v[92:95]
	v_mfma_f32_16x16x32_bf16 v[76:79], v[166:169], v[198:201], v[76:79]
	v_mfma_f32_16x16x32_bf16 v[72:75], v[174:177], v[198:201], v[72:75]
	v_mfma_f32_16x16x32_bf16 v[64:67], v[174:177], v[206:209], v[64:67]
	v_mfma_f32_16x16x32_bf16 v[68:71], v[166:169], v[206:209], v[68:71]
	s_setprio 0
	s_barrier
	s_add_i32 s62, s54, s46
	v_lshl_add_u64 v[210:211], s[38:39], 0, v[130:131]
	s_mov_b32 m0, s62
	ds_read_b128 v[178:181], v145 offset:16384
	ds_read_b128 v[182:185], v145 offset:17408
	ds_read_b128 v[186:189], v145 offset:18432
	ds_read_b128 v[190:193], v145 offset:19456
	ds_read_b128 v[194:197], v145 offset:20480
	ds_read_b128 v[198:201], v145 offset:21504
	ds_read_b128 v[202:205], v145 offset:22528
	ds_read_b128 v[206:209], v145 offset:23552
	global_load_lds_dwordx4 v[210:211], off
	s_add_i32 m0, s62, 0x2000
	s_add_u32 s62, s38, 0x100000
	v_lshl_add_u64 v[212:213], s[38:39], 0, v[128:129]
	s_addc_u32 s63, s39, 0
	s_add_i32 s64, s55, s46
	global_load_lds_dwordx4 v[212:213], off
	v_lshl_add_u64 v[214:215], s[62:63], 0, v[130:131]
	s_mov_b32 m0, s64
	v_lshl_add_u64 v[216:217], s[40:41], 0, v[128:129]
	global_load_lds_dwordx4 v[214:215], off
	v_lshl_add_u64 v[214:215], s[62:63], 0, v[128:129]
	s_add_i32 m0, s64, 0x2000
	s_nop 0
	global_load_lds_dwordx4 v[214:215], off
	v_lshl_add_u64 v[214:215], s[40:41], 0, v[130:131]
	s_mov_b32 m0, s17
	s_nop 0
	global_load_lds_dwordx4 v[214:215], off
	s_mov_b32 m0, s19
	s_nop 0
	global_load_lds_dwordx4 v[216:217], off
	s_waitcnt vmcnt(8)
	s_waitcnt lgkmcnt(0)
	s_barrier
	s_setprio 1
	s_waitcnt lgkmcnt(0)
	v_mfma_f32_16x16x32_bf16 v[60:63], v[146:149], v[178:181], v[60:63]
	v_mfma_f32_16x16x32_bf16 v[56:59], v[154:157], v[178:181], v[56:59]
	v_mfma_f32_16x16x32_bf16 v[48:51], v[154:157], v[186:189], v[48:51]
	v_mfma_f32_16x16x32_bf16 v[52:55], v[146:149], v[186:189], v[52:55]
	v_mfma_f32_16x16x32_bf16 v[40:43], v[146:149], v[194:197], v[40:43]
	v_mfma_f32_16x16x32_bf16 v[32:35], v[154:157], v[194:197], v[32:35]
	v_mfma_f32_16x16x32_bf16 v[16:19], v[154:157], v[202:205], v[16:19]
	v_mfma_f32_16x16x32_bf16 v[24:27], v[146:149], v[202:205], v[24:27]
	v_mfma_f32_16x16x32_bf16 v[60:63], v[150:153], v[182:185], v[60:63]
	v_mfma_f32_16x16x32_bf16 v[56:59], v[158:161], v[182:185], v[56:59]
	v_mfma_f32_16x16x32_bf16 v[48:51], v[158:161], v[190:193], v[48:51]
	v_mfma_f32_16x16x32_bf16 v[52:55], v[150:153], v[190:193], v[52:55]
	v_mfma_f32_16x16x32_bf16 v[40:43], v[150:153], v[198:201], v[40:43]
	v_mfma_f32_16x16x32_bf16 v[32:35], v[158:161], v[198:201], v[32:35]
	v_mfma_f32_16x16x32_bf16 v[16:19], v[158:161], v[206:209], v[16:19]
	v_mfma_f32_16x16x32_bf16 v[24:27], v[150:153], v[206:209], v[24:27]
	s_setprio 0
	s_setprio 1
	v_mfma_f32_16x16x32_bf16 v[44:47], v[162:165], v[178:181], v[44:47]
	v_mfma_f32_16x16x32_bf16 v[36:39], v[170:173], v[178:181], v[36:39]
	v_mfma_f32_16x16x32_bf16 v[20:23], v[170:173], v[186:189], v[20:23]
	v_mfma_f32_16x16x32_bf16 v[28:31], v[162:165], v[186:189], v[28:31]
	v_mfma_f32_16x16x32_bf16 v[12:15], v[162:165], v[194:197], v[12:15]
	v_mfma_f32_16x16x32_bf16 v[8:11], v[170:173], v[194:197], v[8:11]
	v_mfma_f32_16x16x32_bf16 v[0:3], v[170:173], v[202:205], v[0:3]
	v_mfma_f32_16x16x32_bf16 v[4:7], v[162:165], v[202:205], v[4:7]
	v_mfma_f32_16x16x32_bf16 v[44:47], v[166:169], v[182:185], v[44:47]
	v_mfma_f32_16x16x32_bf16 v[36:39], v[174:177], v[182:185], v[36:39]
	v_mfma_f32_16x16x32_bf16 v[20:23], v[174:177], v[190:193], v[20:23]
	v_mfma_f32_16x16x32_bf16 v[28:31], v[166:169], v[190:193], v[28:31]
	v_mfma_f32_16x16x32_bf16 v[12:15], v[166:169], v[198:201], v[12:15]
	v_mfma_f32_16x16x32_bf16 v[8:11], v[174:177], v[198:201], v[8:11]
	v_mfma_f32_16x16x32_bf16 v[0:3], v[174:177], v[206:209], v[0:3]
	v_mfma_f32_16x16x32_bf16 v[4:7], v[166:169], v[206:209], v[4:7]
	s_setprio 0
	s_barrier
	s_add_i32 s62, 0, 0x18000
	s_add_i32 s63, 0, 0x1c000
	v_add_u32_e32 v158, s62, v141
	v_add_u32_e32 v174, s63, v141
	ds_read_b128 v[146:149], v158
	ds_read_b128 v[150:153], v158 offset:1024
	ds_read_b128 v[154:157], v158 offset:2048
	ds_read_b128 v[158:161], v158 offset:3072
	ds_read_b128 v[162:165], v174
	ds_read_b128 v[166:169], v174 offset:1024
	ds_read_b128 v[170:173], v174 offset:2048
	ds_read_b128 v[174:177], v174 offset:3072
	s_add_u32 s40, s40, 0x100000
	s_addc_u32 s41, s41, 0
	s_mov_b32 m0, s48
	v_lshl_add_u64 v[218:219], s[40:41], 0, v[130:131]
	ds_read_b128 v[178:181], v145 offset:32768
	ds_read_b128 v[182:185], v145 offset:33792
	ds_read_b128 v[186:189], v145 offset:34816
	ds_read_b128 v[190:193], v145 offset:35840
	ds_read_b128 v[194:197], v145 offset:36864
	ds_read_b128 v[198:201], v145 offset:37888
	ds_read_b128 v[202:205], v145 offset:38912
	ds_read_b128 v[206:209], v145 offset:39936
	global_load_lds_dwordx4 v[218:219], off
	v_lshl_add_u64 v[218:219], s[40:41], 0, v[128:129]
	s_mov_b32 m0, s49
	s_nop 0
	global_load_lds_dwordx4 v[218:219], off
	s_waitcnt vmcnt(8)
	s_waitcnt lgkmcnt(0)
	s_barrier
	s_setprio 1
	s_waitcnt lgkmcnt(0)
	v_mfma_f32_16x16x32_bf16 v[124:127], v[146:149], v[178:181], v[124:127]
	v_mfma_f32_16x16x32_bf16 v[120:123], v[154:157], v[178:181], v[120:123]
	v_mfma_f32_16x16x32_bf16 v[112:115], v[154:157], v[186:189], v[112:115]
	v_mfma_f32_16x16x32_bf16 v[116:119], v[146:149], v[186:189], v[116:119]
	v_mfma_f32_16x16x32_bf16 v[100:103], v[146:149], v[194:197], v[100:103]
	v_mfma_f32_16x16x32_bf16 v[96:99], v[154:157], v[194:197], v[96:99]
	v_mfma_f32_16x16x32_bf16 v[80:83], v[154:157], v[202:205], v[80:83]
	v_mfma_f32_16x16x32_bf16 v[84:87], v[146:149], v[202:205], v[84:87]
	v_mfma_f32_16x16x32_bf16 v[124:127], v[150:153], v[182:185], v[124:127]
	v_mfma_f32_16x16x32_bf16 v[120:123], v[158:161], v[182:185], v[120:123]
	v_mfma_f32_16x16x32_bf16 v[112:115], v[158:161], v[190:193], v[112:115]
	v_mfma_f32_16x16x32_bf16 v[116:119], v[150:153], v[190:193], v[116:119]
	v_mfma_f32_16x16x32_bf16 v[100:103], v[150:153], v[198:201], v[100:103]
	v_mfma_f32_16x16x32_bf16 v[96:99], v[158:161], v[198:201], v[96:99]
	v_mfma_f32_16x16x32_bf16 v[80:83], v[158:161], v[206:209], v[80:83]
	v_mfma_f32_16x16x32_bf16 v[84:87], v[150:153], v[206:209], v[84:87]
	s_setprio 0
	s_setprio 1
	v_mfma_f32_16x16x32_bf16 v[108:111], v[162:165], v[178:181], v[108:111]
	v_mfma_f32_16x16x32_bf16 v[104:107], v[170:173], v[178:181], v[104:107]
	v_mfma_f32_16x16x32_bf16 v[88:91], v[170:173], v[186:189], v[88:91]
	v_mfma_f32_16x16x32_bf16 v[92:95], v[162:165], v[186:189], v[92:95]
	v_mfma_f32_16x16x32_bf16 v[76:79], v[162:165], v[194:197], v[76:79]
	v_mfma_f32_16x16x32_bf16 v[72:75], v[170:173], v[194:197], v[72:75]
	v_mfma_f32_16x16x32_bf16 v[64:67], v[170:173], v[202:205], v[64:67]
	v_mfma_f32_16x16x32_bf16 v[68:71], v[162:165], v[202:205], v[68:71]
	v_mfma_f32_16x16x32_bf16 v[108:111], v[166:169], v[182:185], v[108:111]
	v_mfma_f32_16x16x32_bf16 v[104:107], v[174:177], v[182:185], v[104:107]
	v_mfma_f32_16x16x32_bf16 v[88:91], v[174:177], v[190:193], v[88:91]
	v_mfma_f32_16x16x32_bf16 v[92:95], v[166:169], v[190:193], v[92:95]
	v_mfma_f32_16x16x32_bf16 v[76:79], v[166:169], v[198:201], v[76:79]
	v_mfma_f32_16x16x32_bf16 v[72:75], v[174:177], v[198:201], v[72:75]
	v_mfma_f32_16x16x32_bf16 v[64:67], v[174:177], v[206:209], v[64:67]
	v_mfma_f32_16x16x32_bf16 v[68:71], v[166:169], v[206:209], v[68:71]
	s_setprio 0
	s_barrier
	s_add_i32 s40, s62, s46
	v_lshl_add_u64 v[210:211], v[210:211], 0, s[14:15]
	s_mov_b32 m0, s40
	ds_read_b128 v[178:181], v145 offset:49152
	ds_read_b128 v[182:185], v145 offset:50176
	ds_read_b128 v[186:189], v145 offset:51200
	ds_read_b128 v[190:193], v145 offset:52224
	ds_read_b128 v[194:197], v145 offset:53248
	ds_read_b128 v[198:201], v145 offset:54272
	ds_read_b128 v[202:205], v145 offset:55296
	ds_read_b128 v[206:209], v145 offset:56320
	global_load_lds_dwordx4 v[210:211], off
	s_add_i32 m0, s40, 0x2000
	s_add_u32 s38, s38, 0x100080
	v_lshl_add_u64 v[210:211], v[212:213], 0, s[14:15]
	s_addc_u32 s39, s39, 0
	s_add_i32 s40, s63, s46
	global_load_lds_dwordx4 v[210:211], off
	v_lshl_add_u64 v[210:211], s[38:39], 0, v[130:131]
	s_mov_b32 m0, s40
	s_nop 0
	global_load_lds_dwordx4 v[210:211], off
	v_lshl_add_u64 v[210:211], s[38:39], 0, v[128:129]
	s_add_i32 m0, s40, 0x2000
	s_nop 0
	global_load_lds_dwordx4 v[210:211], off
	v_lshl_add_u64 v[210:211], v[214:215], 0, s[14:15]
	s_mov_b32 m0, s51
	s_nop 0
	global_load_lds_dwordx4 v[210:211], off
	v_lshl_add_u64 v[210:211], v[216:217], 0, s[14:15]
	s_mov_b32 m0, s52
	s_nop 0
	global_load_lds_dwordx4 v[210:211], off
	s_waitcnt vmcnt(8)
	s_waitcnt lgkmcnt(0)
	s_barrier
	s_setprio 1
	s_waitcnt lgkmcnt(0)
	v_mfma_f32_16x16x32_bf16 v[60:63], v[146:149], v[178:181], v[60:63]
	v_mfma_f32_16x16x32_bf16 v[56:59], v[154:157], v[178:181], v[56:59]
	v_mfma_f32_16x16x32_bf16 v[48:51], v[154:157], v[186:189], v[48:51]
	v_mfma_f32_16x16x32_bf16 v[52:55], v[146:149], v[186:189], v[52:55]
	v_mfma_f32_16x16x32_bf16 v[40:43], v[146:149], v[194:197], v[40:43]
	v_mfma_f32_16x16x32_bf16 v[32:35], v[154:157], v[194:197], v[32:35]
	v_mfma_f32_16x16x32_bf16 v[16:19], v[154:157], v[202:205], v[16:19]
	v_mfma_f32_16x16x32_bf16 v[24:27], v[146:149], v[202:205], v[24:27]
	v_mfma_f32_16x16x32_bf16 v[60:63], v[150:153], v[182:185], v[60:63]
	v_mfma_f32_16x16x32_bf16 v[56:59], v[158:161], v[182:185], v[56:59]
	v_mfma_f32_16x16x32_bf16 v[48:51], v[158:161], v[190:193], v[48:51]
	v_mfma_f32_16x16x32_bf16 v[52:55], v[150:153], v[190:193], v[52:55]
	v_mfma_f32_16x16x32_bf16 v[40:43], v[150:153], v[198:201], v[40:43]
	v_mfma_f32_16x16x32_bf16 v[32:35], v[158:161], v[198:201], v[32:35]
	v_mfma_f32_16x16x32_bf16 v[16:19], v[158:161], v[206:209], v[16:19]
	v_mfma_f32_16x16x32_bf16 v[24:27], v[150:153], v[206:209], v[24:27]
	s_setprio 0
	s_setprio 1
	v_mfma_f32_16x16x32_bf16 v[44:47], v[162:165], v[178:181], v[44:47]
	v_mfma_f32_16x16x32_bf16 v[36:39], v[170:173], v[178:181], v[36:39]
	v_mfma_f32_16x16x32_bf16 v[20:23], v[170:173], v[186:189], v[20:23]
	v_mfma_f32_16x16x32_bf16 v[28:31], v[162:165], v[186:189], v[28:31]
	v_mfma_f32_16x16x32_bf16 v[12:15], v[162:165], v[194:197], v[12:15]
	v_mfma_f32_16x16x32_bf16 v[8:11], v[170:173], v[194:197], v[8:11]
	v_mfma_f32_16x16x32_bf16 v[0:3], v[170:173], v[202:205], v[0:3]
	v_mfma_f32_16x16x32_bf16 v[4:7], v[162:165], v[202:205], v[4:7]
	v_mfma_f32_16x16x32_bf16 v[44:47], v[166:169], v[182:185], v[44:47]
	v_mfma_f32_16x16x32_bf16 v[36:39], v[174:177], v[182:185], v[36:39]
	v_mfma_f32_16x16x32_bf16 v[20:23], v[174:177], v[190:193], v[20:23]
	v_mfma_f32_16x16x32_bf16 v[28:31], v[166:169], v[190:193], v[28:31]
	v_mfma_f32_16x16x32_bf16 v[12:15], v[166:169], v[198:201], v[12:15]
	v_mfma_f32_16x16x32_bf16 v[8:11], v[174:177], v[198:201], v[8:11]
	v_mfma_f32_16x16x32_bf16 v[0:3], v[174:177], v[206:209], v[0:3]
	v_mfma_f32_16x16x32_bf16 v[4:7], v[166:169], v[206:209], v[4:7]
	s_setprio 0
	s_barrier
	s_add_i32 s61, s61, 2
	s_add_u32 s59, s59, 0x100
	s_addc_u32 s60, s60, 0
	s_add_u32 s36, s36, 0x100
	s_addc_u32 s37, s37, 0
	s_cmp_gt_u32 s61, 5
	s_cbranch_scc0 .LBB0_1945
	s_and_b64 vcc, exec, s[20:21]
	s_cbranch_vccz .LBB0_1948
	s_barrier

.LBB0_3161:
	ds_read_b128 v[152:155], v149
	ds_read_b128 v[156:159], v149 offset:1024
	ds_read_b128 v[160:163], v149 offset:2048
	ds_read_b128 v[164:167], v149 offset:3072
	ds_read_b128 v[168:171], v150
	ds_read_b128 v[172:175], v150 offset:1024
	ds_read_b128 v[176:179], v150 offset:2048
	ds_read_b128 v[180:183], v150 offset:3072
	s_add_u32 s36, s34, 0xffc00080
	s_addc_u32 s37, s35, -1
	s_cmpk_eq_i32 s64, 0xfc
	s_cselect_b32 s39, s25, s37
	s_cselect_b32 s38, s60, s36
	s_cselect_b32 s37, s23, s63
	s_cselect_b32 s36, s61, s62
	v_lshl_add_u64 v[144:145], s[34:35], 0, v[138:139]
	s_add_i32 m0, s31, 0xc000
	ds_read_b128 v[184:187], v151
	ds_read_b128 v[188:191], v151 offset:1024
	ds_read_b128 v[192:195], v151 offset:2048
	ds_read_b128 v[196:199], v151 offset:3072
	ds_read_b128 v[200:203], v151 offset:4096
	ds_read_b128 v[204:207], v151 offset:5120
	ds_read_b128 v[208:211], v151 offset:6144
	ds_read_b128 v[212:215], v151 offset:7168
	global_load_lds_dwordx4 v[144:145], off
	v_lshl_add_u64 v[144:145], s[34:35], 0, v[136:137]
	s_add_i32 m0, s31, 0xe000
	s_nop 0
	global_load_lds_dwordx4 v[144:145], off
	s_waitcnt vmcnt(8)
	s_waitcnt lgkmcnt(0)
	s_barrier
	s_setprio 1
	s_waitcnt lgkmcnt(0)
	v_mfma_f32_16x16x32_bf16 v[124:127], v[152:155], v[184:187], v[124:127]
	v_mfma_f32_16x16x32_bf16 v[120:123], v[160:163], v[184:187], v[120:123]
	v_mfma_f32_16x16x32_bf16 v[104:107], v[160:163], v[192:195], v[104:107]
	v_mfma_f32_16x16x32_bf16 v[112:115], v[152:155], v[192:195], v[112:115]
	v_mfma_f32_16x16x32_bf16 v[96:99], v[152:155], v[200:203], v[96:99]
	v_mfma_f32_16x16x32_bf16 v[88:91], v[160:163], v[200:203], v[88:91]
	v_mfma_f32_16x16x32_bf16 v[72:75], v[160:163], v[208:211], v[72:75]
	v_mfma_f32_16x16x32_bf16 v[80:83], v[152:155], v[208:211], v[80:83]
	v_mfma_f32_16x16x32_bf16 v[124:127], v[156:159], v[188:191], v[124:127]
	v_mfma_f32_16x16x32_bf16 v[120:123], v[164:167], v[188:191], v[120:123]
	v_mfma_f32_16x16x32_bf16 v[104:107], v[164:167], v[196:199], v[104:107]
	v_mfma_f32_16x16x32_bf16 v[112:115], v[156:159], v[196:199], v[112:115]
	v_mfma_f32_16x16x32_bf16 v[96:99], v[156:159], v[204:207], v[96:99]
	v_mfma_f32_16x16x32_bf16 v[88:91], v[164:167], v[204:207], v[88:91]
	v_mfma_f32_16x16x32_bf16 v[72:75], v[164:167], v[212:215], v[72:75]
	v_mfma_f32_16x16x32_bf16 v[80:83], v[156:159], v[212:215], v[80:83]
	s_setprio 0
	s_setprio 1
	v_mfma_f32_16x16x32_bf16 v[116:119], v[168:171], v[184:187], v[116:119]
	v_mfma_f32_16x16x32_bf16 v[108:111], v[176:179], v[184:187], v[108:111]
	v_mfma_f32_16x16x32_bf16 v[92:95], v[176:179], v[192:195], v[92:95]
	v_mfma_f32_16x16x32_bf16 v[100:103], v[168:171], v[192:195], v[100:103]
	v_mfma_f32_16x16x32_bf16 v[84:87], v[168:171], v[200:203], v[84:87]
	v_mfma_f32_16x16x32_bf16 v[76:79], v[176:179], v[200:203], v[76:79]
	v_mfma_f32_16x16x32_bf16 v[64:67], v[176:179], v[208:211], v[64:67]
	v_mfma_f32_16x16x32_bf16 v[68:71], v[168:171], v[208:211], v[68:71]
	v_mfma_f32_16x16x32_bf16 v[116:119], v[172:175], v[188:191], v[116:119]
	v_mfma_f32_16x16x32_bf16 v[108:111], v[180:183], v[188:191], v[108:111]
	v_mfma_f32_16x16x32_bf16 v[92:95], v[180:183], v[196:199], v[92:95]
	v_mfma_f32_16x16x32_bf16 v[100:103], v[172:175], v[196:199], v[100:103]
	v_mfma_f32_16x16x32_bf16 v[84:87], v[172:175], v[204:207], v[84:87]
	v_mfma_f32_16x16x32_bf16 v[76:79], v[180:183], v[204:207], v[76:79]
	v_mfma_f32_16x16x32_bf16 v[64:67], v[180:183], v[212:215], v[64:67]
	v_mfma_f32_16x16x32_bf16 v[68:71], v[172:175], v[212:215], v[68:71]
	s_setprio 0
	s_barrier
	s_add_i32 s65, s53, s45
	v_lshl_add_u64 v[144:145], s[36:37], 0, v[130:131]
	s_mov_b32 m0, s65
	ds_read_b128 v[184:187], v151 offset:16384
	ds_read_b128 v[188:191], v151 offset:17408
	ds_read_b128 v[192:195], v151 offset:18432
	ds_read_b128 v[196:199], v151 offset:19456
	ds_read_b128 v[200:203], v151 offset:20480
	ds_read_b128 v[204:207], v151 offset:21504
	ds_read_b128 v[208:211], v151 offset:22528
	ds_read_b128 v[212:215], v151 offset:23552
	global_load_lds_dwordx4 v[144:145], off
	s_add_i32 m0, s65, 0x2000
	s_add_u32 s66, s36, 0x400000
	v_lshl_add_u64 v[216:217], s[36:37], 0, v[134:135]
	s_addc_u32 s67, s37, 0
	s_add_i32 s65, s54, s45
	global_load_lds_dwordx4 v[216:217], off
	v_lshl_add_u64 v[218:219], s[66:67], 0, v[130:131]
	s_mov_b32 m0, s65
	v_lshl_add_u64 v[220:221], s[38:39], 0, v[132:133]
	global_load_lds_dwordx4 v[218:219], off
	v_lshl_add_u64 v[218:219], s[66:67], 0, v[134:135]
	s_add_i32 m0, s65, 0x2000
	s_nop 0
	global_load_lds_dwordx4 v[218:219], off
	v_lshl_add_u64 v[218:219], s[38:39], 0, v[128:129]
	s_mov_b32 m0, s31
	s_nop 0
	global_load_lds_dwordx4 v[218:219], off
	s_mov_b32 m0, s46
	s_nop 0
	global_load_lds_dwordx4 v[220:221], off
	s_waitcnt vmcnt(8)
	s_waitcnt lgkmcnt(0)
	s_barrier
	s_setprio 1
	s_waitcnt lgkmcnt(0)
	v_mfma_f32_16x16x32_bf16 v[60:63], v[152:155], v[184:187], v[60:63]
	v_mfma_f32_16x16x32_bf16 v[56:59], v[160:163], v[184:187], v[56:59]
	v_mfma_f32_16x16x32_bf16 v[40:43], v[160:163], v[192:195], v[40:43]
	v_mfma_f32_16x16x32_bf16 v[44:47], v[152:155], v[192:195], v[44:47]
	v_mfma_f32_16x16x32_bf16 v[28:31], v[152:155], v[200:203], v[28:31]
	v_mfma_f32_16x16x32_bf16 v[24:27], v[160:163], v[200:203], v[24:27]
	v_mfma_f32_16x16x32_bf16 v[8:11], v[160:163], v[208:211], v[8:11]
	v_mfma_f32_16x16x32_bf16 v[12:15], v[152:155], v[208:211], v[12:15]
	v_mfma_f32_16x16x32_bf16 v[60:63], v[156:159], v[188:191], v[60:63]
	v_mfma_f32_16x16x32_bf16 v[56:59], v[164:167], v[188:191], v[56:59]
	v_mfma_f32_16x16x32_bf16 v[40:43], v[164:167], v[196:199], v[40:43]
	v_mfma_f32_16x16x32_bf16 v[44:47], v[156:159], v[196:199], v[44:47]
	v_mfma_f32_16x16x32_bf16 v[28:31], v[156:159], v[204:207], v[28:31]
	v_mfma_f32_16x16x32_bf16 v[24:27], v[164:167], v[204:207], v[24:27]
	v_mfma_f32_16x16x32_bf16 v[8:11], v[164:167], v[212:215], v[8:11]
	v_mfma_f32_16x16x32_bf16 v[12:15], v[156:159], v[212:215], v[12:15]
	s_setprio 0
	s_setprio 1
	v_mfma_f32_16x16x32_bf16 v[52:55], v[168:171], v[184:187], v[52:55]
	v_mfma_f32_16x16x32_bf16 v[48:51], v[176:179], v[184:187], v[48:51]
	v_mfma_f32_16x16x32_bf16 v[32:35], v[176:179], v[192:195], v[32:35]
	v_mfma_f32_16x16x32_bf16 v[36:39], v[168:171], v[192:195], v[36:39]
	v_mfma_f32_16x16x32_bf16 v[20:23], v[168:171], v[200:203], v[20:23]
	v_mfma_f32_16x16x32_bf16 v[16:19], v[176:179], v[200:203], v[16:19]
	v_mfma_f32_16x16x32_bf16 v[0:3], v[176:179], v[208:211], v[0:3]
	v_mfma_f32_16x16x32_bf16 v[4:7], v[168:171], v[208:211], v[4:7]
	v_mfma_f32_16x16x32_bf16 v[52:55], v[172:175], v[188:191], v[52:55]
	v_mfma_f32_16x16x32_bf16 v[48:51], v[180:183], v[188:191], v[48:51]
	v_mfma_f32_16x16x32_bf16 v[32:35], v[180:183], v[196:199], v[32:35]
	v_mfma_f32_16x16x32_bf16 v[36:39], v[172:175], v[196:199], v[36:39]
	v_mfma_f32_16x16x32_bf16 v[20:23], v[172:175], v[204:207], v[20:23]
	v_mfma_f32_16x16x32_bf16 v[16:19], v[180:183], v[204:207], v[16:19]
	v_mfma_f32_16x16x32_bf16 v[0:3], v[180:183], v[212:215], v[0:3]
	v_mfma_f32_16x16x32_bf16 v[4:7], v[172:175], v[212:215], v[4:7]
	s_setprio 0
	s_barrier
	s_add_i32 s65, 0, 0x18000
	s_add_i32 s66, 0, 0x1c000
	v_add_u32_e32 v164, s65, v147
	v_add_u32_e32 v180, s66, v147
	ds_read_b128 v[152:155], v164
	ds_read_b128 v[156:159], v164 offset:1024
	ds_read_b128 v[160:163], v164 offset:2048
	ds_read_b128 v[164:167], v164 offset:3072
	ds_read_b128 v[168:171], v180
	ds_read_b128 v[172:175], v180 offset:1024
	ds_read_b128 v[176:179], v180 offset:2048
	ds_read_b128 v[180:183], v180 offset:3072
	s_add_u32 s38, s38, 0x400000
	s_addc_u32 s39, s39, 0
	s_mov_b32 m0, s47
	v_lshl_add_u64 v[222:223], s[38:39], 0, v[128:129]
	ds_read_b128 v[184:187], v151 offset:32768
	ds_read_b128 v[188:191], v151 offset:33792
	ds_read_b128 v[192:195], v151 offset:34816
	ds_read_b128 v[196:199], v151 offset:35840
	ds_read_b128 v[200:203], v151 offset:36864
	ds_read_b128 v[204:207], v151 offset:37888
	ds_read_b128 v[208:211], v151 offset:38912
	ds_read_b128 v[212:215], v151 offset:39936
	global_load_lds_dwordx4 v[222:223], off
	v_lshl_add_u64 v[222:223], s[38:39], 0, v[132:133]
	s_mov_b32 m0, s48
	s_nop 0
	global_load_lds_dwordx4 v[222:223], off
	s_waitcnt vmcnt(8)
	s_waitcnt lgkmcnt(0)
	s_barrier
	s_setprio 1
	s_waitcnt lgkmcnt(0)
	v_mfma_f32_16x16x32_bf16 v[124:127], v[152:155], v[184:187], v[124:127]
	v_mfma_f32_16x16x32_bf16 v[120:123], v[160:163], v[184:187], v[120:123]
	v_mfma_f32_16x16x32_bf16 v[104:107], v[160:163], v[192:195], v[104:107]
	v_mfma_f32_16x16x32_bf16 v[112:115], v[152:155], v[192:195], v[112:115]
	v_mfma_f32_16x16x32_bf16 v[96:99], v[152:155], v[200:203], v[96:99]
	v_mfma_f32_16x16x32_bf16 v[88:91], v[160:163], v[200:203], v[88:91]
	v_mfma_f32_16x16x32_bf16 v[72:75], v[160:163], v[208:211], v[72:75]
	v_mfma_f32_16x16x32_bf16 v[80:83], v[152:155], v[208:211], v[80:83]
	v_mfma_f32_16x16x32_bf16 v[124:127], v[156:159], v[188:191], v[124:127]
	v_mfma_f32_16x16x32_bf16 v[120:123], v[164:167], v[188:191], v[120:123]
	v_mfma_f32_16x16x32_bf16 v[104:107], v[164:167], v[196:199], v[104:107]
	v_mfma_f32_16x16x32_bf16 v[112:115], v[156:159], v[196:199], v[112:115]
	v_mfma_f32_16x16x32_bf16 v[96:99], v[156:159], v[204:207], v[96:99]
	v_mfma_f32_16x16x32_bf16 v[88:91], v[164:167], v[204:207], v[88:91]
	v_mfma_f32_16x16x32_bf16 v[72:75], v[164:167], v[212:215], v[72:75]
	v_mfma_f32_16x16x32_bf16 v[80:83], v[156:159], v[212:215], v[80:83]
	s_setprio 0
	s_setprio 1
	v_mfma_f32_16x16x32_bf16 v[116:119], v[168:171], v[184:187], v[116:119]
	v_mfma_f32_16x16x32_bf16 v[108:111], v[176:179], v[184:187], v[108:111]
	v_mfma_f32_16x16x32_bf16 v[92:95], v[176:179], v[192:195], v[92:95]
	v_mfma_f32_16x16x32_bf16 v[100:103], v[168:171], v[192:195], v[100:103]
	v_mfma_f32_16x16x32_bf16 v[84:87], v[168:171], v[200:203], v[84:87]
	v_mfma_f32_16x16x32_bf16 v[76:79], v[176:179], v[200:203], v[76:79]
	v_mfma_f32_16x16x32_bf16 v[64:67], v[176:179], v[208:211], v[64:67]
	v_mfma_f32_16x16x32_bf16 v[68:71], v[168:171], v[208:211], v[68:71]
	v_mfma_f32_16x16x32_bf16 v[116:119], v[172:175], v[188:191], v[116:119]
	v_mfma_f32_16x16x32_bf16 v[108:111], v[180:183], v[188:191], v[108:111]
	v_mfma_f32_16x16x32_bf16 v[92:95], v[180:183], v[196:199], v[92:95]
	v_mfma_f32_16x16x32_bf16 v[100:103], v[172:175], v[196:199], v[100:103]
	v_mfma_f32_16x16x32_bf16 v[84:87], v[172:175], v[204:207], v[84:87]
	v_mfma_f32_16x16x32_bf16 v[76:79], v[180:183], v[204:207], v[76:79]
	v_mfma_f32_16x16x32_bf16 v[64:67], v[180:183], v[212:215], v[64:67]
	v_mfma_f32_16x16x32_bf16 v[68:71], v[172:175], v[212:215], v[68:71]
	s_setprio 0
	s_barrier
	s_add_i32 s38, s65, s45
	v_lshl_add_u64 v[144:145], v[144:145], 0, s[10:11]
	s_mov_b32 m0, s38
	ds_read_b128 v[184:187], v151 offset:49152
	ds_read_b128 v[188:191], v151 offset:50176
	ds_read_b128 v[192:195], v151 offset:51200
	ds_read_b128 v[196:199], v151 offset:52224
	ds_read_b128 v[200:203], v151 offset:53248
	ds_read_b128 v[204:207], v151 offset:54272
	ds_read_b128 v[208:211], v151 offset:55296
	ds_read_b128 v[212:215], v151 offset:56320
	global_load_lds_dwordx4 v[144:145], off
	s_add_i32 m0, s38, 0x2000
	s_add_u32 s36, s36, 0x400080
	v_lshl_add_u64 v[144:145], v[216:217], 0, s[10:11]
	s_addc_u32 s37, s37, 0
	s_add_i32 s38, s66, s45
	global_load_lds_dwordx4 v[144:145], off
	v_lshl_add_u64 v[144:145], s[36:37], 0, v[130:131]
	s_mov_b32 m0, s38
	s_nop 0
	global_load_lds_dwordx4 v[144:145], off
	v_lshl_add_u64 v[144:145], s[36:37], 0, v[134:135]
	s_add_i32 m0, s38, 0x2000
	s_nop 0
	global_load_lds_dwordx4 v[144:145], off
	v_lshl_add_u64 v[144:145], v[218:219], 0, s[10:11]
	s_mov_b32 m0, s50
	s_nop 0
	global_load_lds_dwordx4 v[144:145], off
	v_lshl_add_u64 v[144:145], v[220:221], 0, s[10:11]
	s_mov_b32 m0, s51
	s_nop 0
	global_load_lds_dwordx4 v[144:145], off
	s_waitcnt vmcnt(8)
	s_waitcnt lgkmcnt(0)
	s_barrier
	s_setprio 1
	s_waitcnt lgkmcnt(0)
	v_mfma_f32_16x16x32_bf16 v[60:63], v[152:155], v[184:187], v[60:63]
	v_mfma_f32_16x16x32_bf16 v[56:59], v[160:163], v[184:187], v[56:59]
	v_mfma_f32_16x16x32_bf16 v[40:43], v[160:163], v[192:195], v[40:43]
	v_mfma_f32_16x16x32_bf16 v[44:47], v[152:155], v[192:195], v[44:47]
	v_mfma_f32_16x16x32_bf16 v[28:31], v[152:155], v[200:203], v[28:31]
	v_mfma_f32_16x16x32_bf16 v[24:27], v[160:163], v[200:203], v[24:27]
	v_mfma_f32_16x16x32_bf16 v[8:11], v[160:163], v[208:211], v[8:11]
	v_mfma_f32_16x16x32_bf16 v[12:15], v[152:155], v[208:211], v[12:15]
	v_mfma_f32_16x16x32_bf16 v[60:63], v[156:159], v[188:191], v[60:63]
	v_mfma_f32_16x16x32_bf16 v[56:59], v[164:167], v[188:191], v[56:59]
	v_mfma_f32_16x16x32_bf16 v[40:43], v[164:167], v[196:199], v[40:43]
	v_mfma_f32_16x16x32_bf16 v[44:47], v[156:159], v[196:199], v[44:47]
	v_mfma_f32_16x16x32_bf16 v[28:31], v[156:159], v[204:207], v[28:31]
	v_mfma_f32_16x16x32_bf16 v[24:27], v[164:167], v[204:207], v[24:27]
	v_mfma_f32_16x16x32_bf16 v[8:11], v[164:167], v[212:215], v[8:11]
	v_mfma_f32_16x16x32_bf16 v[12:15], v[156:159], v[212:215], v[12:15]
	s_setprio 0
	s_setprio 1
	v_mfma_f32_16x16x32_bf16 v[52:55], v[168:171], v[184:187], v[52:55]
	v_mfma_f32_16x16x32_bf16 v[48:51], v[176:179], v[184:187], v[48:51]
	v_mfma_f32_16x16x32_bf16 v[32:35], v[176:179], v[192:195], v[32:35]
	v_mfma_f32_16x16x32_bf16 v[36:39], v[168:171], v[192:195], v[36:39]
	v_mfma_f32_16x16x32_bf16 v[20:23], v[168:171], v[200:203], v[20:23]
	v_mfma_f32_16x16x32_bf16 v[16:19], v[176:179], v[200:203], v[16:19]
	v_mfma_f32_16x16x32_bf16 v[0:3], v[176:179], v[208:211], v[0:3]
	v_mfma_f32_16x16x32_bf16 v[4:7], v[168:171], v[208:211], v[4:7]
	v_mfma_f32_16x16x32_bf16 v[52:55], v[172:175], v[188:191], v[52:55]
	v_mfma_f32_16x16x32_bf16 v[48:51], v[180:183], v[188:191], v[48:51]
	v_mfma_f32_16x16x32_bf16 v[32:35], v[180:183], v[196:199], v[32:35]
	v_mfma_f32_16x16x32_bf16 v[36:39], v[172:175], v[196:199], v[36:39]
	v_mfma_f32_16x16x32_bf16 v[20:23], v[172:175], v[204:207], v[20:23]
	v_mfma_f32_16x16x32_bf16 v[16:19], v[180:183], v[204:207], v[16:19]
	v_mfma_f32_16x16x32_bf16 v[0:3], v[180:183], v[212:215], v[0:3]
	v_mfma_f32_16x16x32_bf16 v[4:7], v[172:175], v[212:215], v[4:7]
	s_setprio 0
	s_barrier
	s_add_i32 s64, s64, 2
	s_add_u32 s62, s62, 0x100
	s_addc_u32 s63, s63, 0
	s_add_u32 s34, s34, 0x100
	s_addc_u32 s35, s35, 0
	s_cmpk_gt_u32 s64, 0xfd
	s_cbranch_scc0 .LBB0_3161
	s_and_b64 vcc, exec, s[12:13]
	s_cbranch_vccz .LBB0_3164
	s_barrier
